# RWKV units: OPt token-group index XOR key=(row>>5)&1: stage-H ds_write_b16 stores 4-way -> 2-way bank conflicts, chain readers (kt>=2, vt4) apply the same key
# speedup vs baseline: 1.0365x; 1.0010x over previous
.LBB0_355:
	v_mov_b32_e32 v23, s47
	v_mov_b32_e32 v24, s45
	v_cndmask_b32_e64 v25, v23, v24, s[2:3]
	v_mov_b32_e32 v23, s46
	v_mov_b32_e32 v24, s44
	v_cndmask_b32_e64 v24, v23, v24, s[2:3]
	v_lshlrev_b32_e32 v23, 1, v64
	v_bfe_u32 v28, v64, 5, 1
	v_and_b32_e32 v29, 62, v23
	v_lshl_or_b32 v23, v28, 6, v29
	v_readlane_b32 s6, v255, 38
	v_lshlrev_b32_e32 v30, 2, v29
	v_readlane_b32 s7, v255, 39
	v_mad_u32_u24 v178, v23, 40, s6
	v_lshlrev_b32_e32 v23, 8, v28
	v_lshlrev_b32_e32 v31, 1, v122
	v_add3_u32 v179, s7, v23, v30
	v_lshl_add_u32 v180, v122, 2, s7
	v_add_u32_e32 v32, s6, v31
	v_readlane_b32 s6, v255, 28
	v_readlane_b32 s7, v255, 29
	v_lshl_add_u64 v[24:25], v[2:3], 1, v[24:25]
	s_lshl_b32 s6, s26, 5
	s_mov_b32 s9, s7
	v_writelane_b32 v255, s8, 28
	v_lshl_add_u64 v[24:25], v[24:25], 0, s[6:7]
	v_lshlrev_b32_e32 v26, 1, v63
	v_mov_b32_e32 v27, v3
	v_writelane_b32 v255, s9, 29
	v_lshl_add_u64 v[126:127], v[24:25], 0, v[26:27]
	v_lshlrev_b32_e32 v23, 1, v124
	v_lshlrev_b32_e32 v26, 1, v22
	v_add3_u32 v181, 0, v23, v26
	v_or3_b32 v2, v2, v21, v122
	v_lshlrev_b32_e32 v22, 2, v108
	v_mov_b32_e32 v23, v3
	v_mul_u32_u24_e32 v21, 0x900, v28
	v_lshlrev_b32_e32 v27, 1, v29
	v_readlane_b32 s27, v255, 40
	v_lshl_add_u64 v[128:129], v[40:41], 0, v[22:23]
	v_cmp_eq_u32_e32 vcc, v122, v63
	v_add3_u32 v183, s27, v21, v27
	v_lshl_or_b32 v21, v28, 4, 1
	v_or_b32_e32 v22, 1, v122
	v_lshlrev_b32_e32 v184, 6, v21
	v_mul_u32_u24_e32 v21, 0x90, v21
	v_cndmask_b32_e64 v215, 0, 1.0, vcc
	v_cmp_lt_u32_e64 s[14:15], v22, v63
	v_cmp_eq_u32_e32 vcc, v22, v63
	v_or_b32_e32 v22, 2, v122
	v_add3_u32 v185, s27, v21, v27
	v_add_u32_e32 v21, s27, v26
	v_lshlrev_b32_e32 v20, 1, v20
	v_cndmask_b32_e64 v217, 0, 1.0, vcc
	v_cmp_lt_u32_e64 s[16:17], v22, v63
	v_cmp_lt_u32_e64 s[18:19], v63, v22
	v_cmp_eq_u32_e32 vcc, v22, v63
	v_or_b32_e32 v22, 3, v122
	v_add_u32_e32 v214, v21, v20
	v_cndmask_b32_e64 v218, 0, 1.0, vcc
	v_cmp_lt_u32_e64 s[20:21], v22, v63
	v_cmp_lt_u32_e64 s[22:23], v63, v22
	v_cmp_eq_u32_e32 vcc, v22, v63
	v_add_u32_e32 v220, v21, v31
	v_or_b32_e32 v21, 16, v63
	v_mov_b32_e32 v22, s27
	v_mad_u32_u24 v21, v21, s92, v22
	v_readlane_b32 s36, v254, 53
	v_add_u32_e32 v226, v21, v20
	v_lshlrev_b32_e32 v20, 12, v28
	v_lshlrev_b64 v[0:1], 2, v[0:1]
	v_readlane_b32 s38, v254, 55
	v_readlane_b32 s39, v254, 56
	v_readlane_b32 s42, v254, 59
	v_readlane_b32 s43, v254, 60
	v_add_u32_e32 v227, v21, v31
	v_add3_u32 v232, 0, v30, v20
	v_readlane_b32 s46, v254, 63
	v_readlane_b32 s47, v255, 0
	v_readlane_b32 s48, v255, 1
	v_readlane_b32 s49, v255, 2
	v_readlane_b32 s50, v255, 3
	v_readlane_b32 s51, v255, 4
	v_lshl_add_u64 v[20:21], s[38:39], 0, v[0:1]
	v_lshl_add_u64 v[0:1], s[42:43], 0, v[0:1]
	v_lshlrev_b64 v[22:23], 2, v[2:3]
	v_or_b32_e32 v24, 16, v2
	v_mov_b32_e32 v25, v3
	v_lshl_or_b32 v216, s26, 4, v63
	v_mul_u32_u24_e32 v26, 40, v63
	v_readlane_b32 s37, v254, 54
	v_readlane_b32 s40, v254, 57
	v_readlane_b32 s41, v254, 58
	v_readlane_b32 s44, v254, 61
	v_readlane_b32 s45, v254, 62
	v_lshl_add_u64 v[130:131], v[20:21], 0, v[22:23]
	v_lshl_add_u64 v[132:133], v[0:1], 0, v[22:23]
	v_lshl_add_u64 v[134:135], s[46:47], 0, v[22:23]
	v_lshl_add_u64 v[136:137], s[48:49], 0, v[22:23]
	v_lshl_add_u64 v[138:139], s[50:51], 0, v[22:23]
	v_mov_b32_e32 v22, v3
	v_mov_b32_e32 v23, v3
	v_bfe_u32 v176, v64, 6, 2
	v_lshlrev_b32_e32 v177, 10, v28
	v_mad_u32_u24 v221, v216, 40, v32
	v_mad_u32_u24 v222, v63, 40, v32
	v_add_u32_e32 v233, 0, v27
	v_mov_b32_e32 v20, v3
	v_mov_b32_e32 v21, v3
	v_add_u32_e32 v236, v32, v26
	v_lshlrev_b64 v[142:143], 1, v[24:25]
	v_mov_b64_e32 v[34:35], v[22:23]
	v_mov_b64_e32 v[30:31], v[22:23]
	v_mov_b64_e32 v[26:27], v[22:23]
	v_readlane_b32 s36, v255, 5
	s_mov_b32 s76, 0
	v_cmp_eq_u32_e64 s[4:5], 0, v176
	v_add_u32_e32 v182, 0xe000, v181
	v_cmp_gt_u32_e64 s[6:7], 8, v63
	v_cmp_eq_u32_e64 s[8:9], v66, v65
	v_mov_b32_e32 v109, v3
	v_or_b32_e32 v186, 0x80, v177
	v_add_u32_e32 v187, 0x90, v185
	v_or_b32_e32 v188, 0xc0, v177
	v_add_u32_e32 v189, 0x120, v185
	v_or_b32_e32 v190, 0x100, v177
	v_add_u32_e32 v191, 0x1b0, v185
	v_or_b32_e32 v192, 0x140, v177
	v_add_u32_e32 v193, 0x240, v185
	v_or_b32_e32 v194, 0x180, v177
	v_add_u32_e32 v195, 0x2d0, v185
	v_or_b32_e32 v196, 0x1c0, v177
	v_add_u32_e32 v197, 0x360, v185
	v_or_b32_e32 v198, 0x200, v177
	v_add_u32_e32 v199, 0x3f0, v185
	v_or_b32_e32 v200, 0x240, v177
	v_add_u32_e32 v201, 0x480, v185
	v_or_b32_e32 v202, 0x280, v177
	v_add_u32_e32 v203, 0x510, v185
	v_or_b32_e32 v204, 0x2c0, v177
	v_add_u32_e32 v205, 0x5a0, v185
	v_or_b32_e32 v206, 0x300, v177
	v_add_u32_e32 v207, 0x630, v185
	v_or_b32_e32 v208, 0x340, v177
	v_add_u32_e32 v209, 0x6c0, v185
	v_or_b32_e32 v210, 0x380, v177
	v_add_u32_e32 v211, 0x750, v185
	v_or_b32_e32 v212, 0x3c0, v177
	v_add_u32_e32 v213, 0x7e0, v185
	v_and_b32_e32 v244, 31, v238
	v_lshlrev_b32_e32 v244, 1, v244
	v_xor_b32_e32 v245, 4, v244
	v_sub_u32_e32 v245, v245, v244
	v_xor_b32_e32 v246, 8, v244
	v_sub_u32_e32 v246, v246, v244
	v_xor_b32_e32 v247, 12, v244
	v_sub_u32_e32 v247, v247, v244
	v_add_u32_e32 v186, v186, v245
	v_add_u32_e32 v188, v188, v245
	v_add_u32_e32 v190, v190, v246
	v_add_u32_e32 v192, v192, v246
	v_add_u32_e32 v194, v194, v247
	v_add_u32_e32 v196, v196, v247
	v_add_u32_e32 v202, v202, v245
	v_add_u32_e32 v204, v204, v245
	v_add_u32_e32 v206, v206, v246
	v_add_u32_e32 v208, v208, v246
	v_add_u32_e32 v210, v210, v247
	v_add_u32_e32 v212, v212, v247
	v_cmp_lt_u32_e64 s[10:11], v122, v63
	v_cmp_lt_u32_e64 s[12:13], v63, v122
	v_cndmask_b32_e64 v219, 0, 1.0, vcc
	v_add_u32_e32 v223, 0x280, v222
	v_add_u32_e32 v224, 0x500, v222
	v_add_u32_e32 v225, 0x780, v222
	v_add_u32_e32 v228, 0xa00, v222
	v_add_u32_e32 v229, 0xc80, v222
	v_add_u32_e32 v230, 0xf00, v222
	v_add_u32_e32 v231, 0x1180, v222
	v_bfe_u32 v244, v238, 4, 2
	v_xor_b32_e32 v245, 1, v244
	v_sub_u32_e32 v245, v245, v244
	v_lshlrev_b32_e32 v245, 3, v245
	v_add_u32_e32 v224, v224, v245
	v_add_u32_e32 v225, v225, v245
	v_add_u32_e32 v230, v230, v245
	v_add_u32_e32 v231, v231, v245
	v_bfe_u32 v246, v238, 7, 1
	v_xor_b32_e32 v247, v244, v246
	v_sub_u32_e32 v247, v247, v244
	v_lshlrev_b32_e32 v247, 3, v247
	v_add_u32_e32 v221, v221, v247
	v_bfe_u32 v246, v238, 4, 1
	v_bfe_u32 v247, v238, 6, 2
	v_xor_b32_e32 v246, v247, v246
	v_sub_u32_e32 v246, v246, v247
	v_lshlrev_b32_e32 v246, 3, v246
	v_add_u32_e32 v178, v178, v246
	v_sub_u32_e32 v234, 0xdf, v172
	v_sub_u32_e32 v235, 0, v62
	s_mov_b32 s77, 64
	v_lshlrev_b64 v[140:141], 1, v[2:3]
	s_mov_b32 s26, 0
	v_mov_b64_e32 v[32:33], v[20:21]
	v_mov_b64_e32 v[28:29], v[20:21]
	v_mov_b64_e32 v[24:25], v[20:21]
	v_readlane_b32 s37, v255, 6
	v_readlane_b32 s38, v255, 7
	v_readlane_b32 s39, v255, 8
	v_readlane_b32 s40, v255, 9
	v_readlane_b32 s41, v255, 10
	v_readlane_b32 s42, v255, 11
	v_readlane_b32 s43, v255, 12
	v_readlane_b32 s44, v255, 13
	v_readlane_b32 s45, v255, 14
	v_readlane_b32 s46, v255, 15
	v_readlane_b32 s47, v255, 16
	v_readlane_b32 s48, v255, 17
	v_readlane_b32 s49, v255, 18
	v_readlane_b32 s50, v255, 19
	v_readlane_b32 s51, v255, 20
	s_waitcnt lgkmcnt(0)
	s_barrier
	s_andn2_b64 vcc, exec, s[24:25]
	s_mov_b64 s[28:29], -1
	s_cbranch_vccnz .LBB0_363

.LBB0_362:
	s_or_b64 exec, exec, s[28:29]
	s_waitcnt lgkmcnt(0)
	s_barrier
	ds_read_b128 v[40:43], v214 offset:9216
	ds_read_b128 v[48:51], v214 offset:18496
	ds_read_b128 v[56:59], v214 offset:9280
	ds_read_b128 v[60:63], v214 offset:23040
	ds_read_b128 v[36:39], v214 offset:18432
	s_nop 0
	s_nop 0
	s_nop 0
	ds_read_b128 v[64:67], v214 offset:13824
	s_waitcnt lgkmcnt(1)
	v_mfma_f32_16x16x32_f16 v[52:55], v[40:43], v[36:39], 0
	s_nop 0
	s_nop 0
	s_nop 0
	ds_read_b128 v[68:71], v214 offset:13888
	ds_read_b128 v[72:75], v214 offset:23104
	v_add_u32_e32 v80, 0x1000, v220
	s_nop 0
	v_mfma_f32_16x16x32_f16 v[52:55], v[56:59], v[48:51], v[52:55]
	v_mov_b32_e32 v82, v3
	v_mov_b32_e32 v83, v3
	v_mov_b32_e32 v86, v3
	v_mfma_f32_16x16x32_f16 v[44:47], v[36:39], v[40:43], 0
	s_nop 3
	v_cvt_f16_f32_e32 v0, v52
	v_cvt_f16_f32_e32 v1, v54
	v_cvt_f16_f32_e32 v2, v55
	v_mfma_f32_16x16x32_f16 v[44:47], v[48:51], v[56:59], v[44:47]
	v_cndmask_b32_e64 v79, 0, v0, s[12:13]
	v_cvt_f16_f32_e32 v0, v53
	v_cndmask_b32_e64 v54, 0, v1, s[18:19]
	s_nop 0
	v_mfma_f32_16x16x32_f16 v[40:43], v[60:63], v[40:43], 0
	v_cndmask_b32_e64 v55, 0, v2, s[22:23]
	s_nop 1
	v_cndmask_b32_e64 v76, 0, v44, s[10:11]
	v_cndmask_b32_e64 v77, 0, v45, s[14:15]
	s_nop 0
	s_waitcnt lgkmcnt(2)
	v_mfma_f32_16x16x32_f16 v[36:39], v[36:39], v[64:67], 0
	v_cndmask_b32_e64 v52, 0, v46, s[16:17]
	v_cndmask_b32_e64 v78, 0, v47, s[20:21]
	v_cndmask_b32_e64 v53, v0, 0, s[10:11]
	v_mfma_f32_16x16x32_f16 v[44:47], v[60:63], v[64:67], 0
	v_cvt_pk_f16_f32 v1, v52, v78
	v_cvt_pk_f16_f32 v0, v76, v77
	v_mov_b32_e32 v2, v3
	s_nop 0
	s_waitcnt lgkmcnt(0)
	v_mfma_f32_16x16x32_f16 v[60:63], v[72:75], v[56:59], v[40:43]
	v_add_f32_e32 v56, v215, v76
	v_add_f32_e32 v57, v217, v77
	v_add_f32_e32 v58, v218, v52
	v_mfma_f32_16x16x32_f16 v[40:43], v[48:51], v[68:71], v[36:39]
	v_add_f32_e32 v59, v219, v78
	v_cvt_pk_f16_f32 v67, v26, v27
	v_cvt_pk_f16_f32 v66, v24, v25
	v_pack_b32_f16 v37, v54, v55
	v_pack_b32_f16 v36, v79, v53
	v_mov_b32_e32 v38, v3
	v_mov_b32_e32 v39, v3
	v_mfma_f32_16x16x32_f16 v[52:55], v[72:75], v[68:71], v[44:47]
	ds_read2_b64 v[68:71], v220 offset0:8 offset1:12
	v_cvt_pk_f16_f32 v65, v30, v31
	v_cvt_pk_f16_f32 v64, v28, v29
	v_mfma_f32_16x16x32_f16 v[48:51], v[0:3], v[36:39], 0
	v_cvt_pk_f16_f32 v45, v58, v59
	v_cvt_pk_f16_f32 v44, v56, v57
	v_mov_b32_e32 v46, v3
	v_mfma_f32_16x16x32_f16 v[36:39], v[36:39], v[0:3], 0
	v_mov_b32_e32 v47, v3
	s_nop 2
	v_cvt_pk_f16_f32 v1, v50, v51
	v_cvt_pk_f16_f32 v0, v48, v49
	v_mov_b32_e32 v50, v3
	v_mov_b32_e32 v51, v3
	v_cvt_pk_f16_f32 v49, v38, v39
	v_cvt_pk_f16_f32 v48, v36, v37
	v_mfma_f32_16x16x32_f16 v[44:47], v[0:3], v[44:47], v[56:59]
	v_mov_b32_e32 v87, v3
	v_mov_b32_e32 v90, v3
	v_mov_b32_e32 v91, v3
	v_mfma_f32_16x16x32_f16 v[36:39], v[48:51], v[0:3], 0
	ds_read2_b64 v[128:131], v220 offset1:4
	v_cvt_pk_f16_f32 v59, v34, v35
	v_cvt_pk_f16_f32 v58, v32, v33
	v_cvt_pk_f16_f32 v57, v22, v23
	v_mfma_f32_16x16x32_f16 v[48:51], v[0:3], v[48:51], 0
	v_cvt_pk_f16_f32 v56, v20, v21
	s_nop 2
	v_cvt_pk_f16_f32 v1, v38, v39
	v_cvt_pk_f16_f32 v0, v36, v37
	v_cvt_pk_f16_f32 v37, v46, v47
	v_cvt_pk_f16_f32 v36, v44, v45
	v_mov_b32_e32 v38, v3
	v_mov_b32_e32 v39, v3
	v_cvt_f16_f32_e32 v52, v52
	s_add_i32 s27, s26, 1
	v_mfma_f32_16x16x32_f16 v[44:47], v[0:3], v[36:39], v[44:47]
	v_cvt_pk_f16_f32 v37, v50, v51
	v_cvt_pk_f16_f32 v36, v48, v49
	v_mov_b32_e32 v50, v3
	v_mov_b32_e32 v51, v3
	v_mfma_f32_16x16x32_f16 v[36:39], v[36:39], v[0:3], 0
	s_nop 2
	v_cvt_pk_f16_f32 v1, v46, v47
	v_cvt_pk_f16_f32 v0, v44, v45
	s_nop 2
	v_cvt_pk_f16_f32 v49, v38, v39
	v_cvt_pk_f16_f32 v48, v36, v37
	s_nop 0
	s_nop 0
	s_waitcnt lgkmcnt(0)
	v_mfma_f32_16x16x32_f16 v[36:39], v[128:131], v[56:59], 0
	v_mfma_f32_16x16x32_f16 v[44:47], v[48:51], v[0:3], v[44:47]
	v_cvt_f16_f32_e32 v0, v60
	v_cvt_f16_f32_e32 v1, v61
	v_cvt_f16_f32_e32 v2, v62
	v_cvt_f16_f32_e32 v48, v63
	v_mfma_f32_16x16x32_f16 v[76:79], v[68:71], v[64:67], v[36:39]
	ds_read2_b64 v[72:75], v80 offset0:64 offset1:68
	ds_read2st64_b64 v[132:135], v221 offset0:20 offset1:25
	ds_read2_b64 v[68:71], v80 offset0:72 offset1:76
	s_nop 0
	s_nop 0
	v_cndmask_b32_e64 v0, 0, v0, s[10:11]
	v_cndmask_b32_e64 v49, 0, v1, s[14:15]
	v_cndmask_b32_e64 v1, 0, v2, s[16:17]
	v_cndmask_b32_e64 v2, 0, v48, s[20:21]
	v_pack_b32_f16 v1, v1, v2
	v_pack_b32_f16 v0, v0, v49
	v_mov_b32_e32 v2, v3
	s_nop 0
	s_waitcnt lgkmcnt(1)
	v_mov_b32_e32 v60, v132
	v_mov_b32_e32 v61, v133
	ds_read2_b64 v[128:131], v236 offset1:80
	v_mov_b32_e32 v62, v3
	v_mov_b32_e32 v63, v3
	v_cvt_f16_f32_e32 v36, v40
	ds_read_b128 v[136:139], v180
	v_cvt_f16_f32_e32 v40, v42
	v_mfma_f32_16x16x32_f16 v[48:51], v[0:3], v[60:63], v[76:79]
	v_cvt_pk_f16_f32 v1, v46, v47
	v_cvt_pk_f16_f32 v0, v44, v45
	v_cvt_f16_f32_e32 v37, v41
	v_mov_b32_e32 v78, v3
	v_mov_b32_e32 v79, v3
	s_nop 2
	v_cvt_pk_f16_f32 v77, v50, v51
	v_cvt_pk_f16_f32 v76, v48, v49
	v_cndmask_b32_e64 v88, v40, 0, s[18:19]
	v_mfma_f32_16x16x32_f16 v[56:59], v[72:75], v[56:59], 0
	v_cndmask_b32_e64 v36, v36, 0, s[12:13]
	v_cndmask_b32_e64 v37, 0, v37, s[10:11]
	v_mov_b32_e32 v74, v3
	v_mfma_f32_16x16x32_f16 v[44:47], v[0:3], v[76:79], 0
	ds_read_b64 v[76:77], v222 offset:5120
	ds_read_b128 v[140:143], v180 offset:64
	v_mov_b32_e32 v75, v3
	s_waitcnt lgkmcnt(4)
	v_mfma_f32_16x16x32_f16 v[56:59], v[68:71], v[64:67], v[56:59]
	s_nop 5
	v_cvt_pk_f16_f32 v1, v46, v47
	v_cvt_pk_f16_f32 v0, v44, v45
	s_nop 0
	s_nop 0
	s_nop 0
	s_nop 0
	s_waitcnt lgkmcnt(3)
	v_mov_b32_e32 v80, v128
	v_mov_b32_e32 v81, v129
	ds_read_b64 v[44:45], v223 offset:5120
	ds_read2_b64 v[144:147], v224 offset1:80
	s_nop 0
	s_waitcnt lgkmcnt(4)
	v_pk_mul_f32 v[50:51], v[22:23], v[138:139]
	v_pk_mul_f32 v[48:49], v[20:21], v[136:137]
	ds_read_b128 v[136:139], v180 offset:128
	s_nop 1
	v_mfma_f32_16x16x32_f16 v[48:51], v[80:83], v[0:3], v[48:51]
	v_cvt_f16_f32_e32 v80, v43
	v_cndmask_b32_e64 v89, v80, 0, s[22:23]
	s_nop 0
	s_waitcnt lgkmcnt(4)
	v_mfma_f32_16x16x32_f16 v[40:43], v[76:79], v[60:63], v[48:51]
	s_nop 3
	s_nop 0
	s_nop 0
	ds_read_b64 v[80:81], v224 offset:5120
	v_mov_b32_e32 v76, v130
	v_mov_b32_e32 v77, v131
	v_mov_b32_e32 v46, v3
	s_nop 0
	s_waitcnt lgkmcnt(4)
	v_pk_mul_f32 v[50:51], v[34:35], v[142:143]
	v_pk_mul_f32 v[48:49], v[32:33], v[140:141]
	v_mov_b32_e32 v47, v3
	ds_read_b128 v[128:131], v180 offset:192
	s_nop 0
	v_mfma_f32_16x16x32_f16 v[48:51], v[76:79], v[0:3], v[48:51]
	s_nop 0
	s_nop 0
	s_waitcnt lgkmcnt(3)
	v_mov_b32_e32 v84, v144
	v_mfma_f32_16x16x32_f16 v[48:51], v[44:47], v[60:63], v[48:51]
	s_nop 0
	s_nop 0
	v_mov_b32_e32 v85, v145
	v_pack_b32_f16 v77, v88, v89
	v_mov_b32_e32 v88, v146
	s_nop 0
	s_waitcnt lgkmcnt(2)
	v_pk_mul_f32 v[46:47], v[30:31], v[138:139]
	v_pk_mul_f32 v[44:45], v[28:29], v[136:137]
	v_mov_b32_e32 v89, v147
	v_pack_b32_f16 v76, v36, v37
	v_mfma_f32_16x16x32_f16 v[44:47], v[84:87], v[0:3], v[44:47]
	ds_read_b64 v[84:85], v225 offset:5120
	v_cndmask_b32_e64 v36, v52, 0, s[12:13]
	v_cvt_f16_f32_e32 v37, v53
	v_cndmask_b32_e64 v37, 0, v37, s[10:11]
	s_nop 0
	s_waitcnt lgkmcnt(2)
	v_mfma_f32_16x16x32_f16 v[44:47], v[80:83], v[60:63], v[44:47]
	s_nop 0
	s_nop 0
	v_pack_b32_f16 v72, v36, v37
	ds_read_b128 v[68:71], v226 offset:9216
	ds_read_b128 v[94:97], v226 offset:9280
	s_nop 0
	s_waitcnt lgkmcnt(3)
	v_pk_mul_f32 v[82:83], v[26:27], v[130:131]
	ds_read_b128 v[64:67], v226 offset:18432
	v_pk_mul_f32 v[80:81], v[24:25], v[128:129]
	s_nop 0
	ds_read_b128 v[98:101], v226 offset:23104
	v_mfma_f32_16x16x32_f16 v[78:81], v[88:91], v[0:3], v[80:83]
	ds_read_b128 v[90:93], v226 offset:18496
	s_nop 1
	v_cvt_f16_f32_e32 v82, v54
	v_cvt_f16_f32_e32 v83, v55
	s_nop 0
	s_waitcnt lgkmcnt(5)
	v_mfma_f32_16x16x32_f16 v[52:55], v[84:87], v[60:63], v[78:81]
	ds_read_b128 v[86:89], v226 offset:13824
	s_nop 1
	v_cndmask_b32_e64 v78, v82, 0, s[18:19]
	v_cndmask_b32_e64 v79, v83, 0, s[22:23]
	v_pack_b32_f16 v73, v78, v79
	v_mov_b32_e32 v78, v3
	v_mov_b32_e32 v79, v3
	v_add_u32_e32 v80, s77, v122
	v_add_u32_e32 v81, s76, v235
	v_mfma_f32_16x16x32_f16 v[56:59], v[76:79], v[0:3], v[56:59]
	ds_read_b128 v[76:79], v226 offset:23040
	v_subrev_u32_e32 v102, 64, v80
	v_add_u32_e32 v0, 0xff, v81
	v_mfma_f32_16x16x32_f16 v[58:61], v[72:75], v[60:63], v[56:59]
	v_cndmask_b32_e64 v0, v0, v102, s[2:3]
	v_add_u32_e32 v0, v0, v173
	v_mad_i64_i32 v[0:1], s[28:29], v0, s91, v[126:127]
	s_nop 0
	s_waitcnt lgkmcnt(4)
	v_mfma_f32_16x16x32_f16 v[82:85], v[68:71], v[64:67], 0
	s_nop 2
	v_cvt_f16_f32_e32 v2, v58
	v_cvt_f16_f32_e32 v60, v60
	ds_read_b128 v[128:131], v226 offset:13888
	global_store_short v[0:1], v2, off
	v_subrev_u32_e32 v0, 63, v80
	v_xad_u32 v1, v102, -2, v166
	v_cvt_f16_f32_e32 v2, v59
	s_nop 0
	v_mfma_f32_16x16x32_f16 v[72:75], v[64:67], v[68:71], 0
	v_cndmask_b32_e64 v0, v1, v0, s[2:3]
	v_add_u32_e32 v0, v0, v173
	v_mad_i64_i32 v[0:1], s[28:29], v0, s91, v[126:127]
	s_nop 0
	s_waitcnt lgkmcnt(2)
	v_mfma_f32_16x16x32_f16 v[62:65], v[64:67], v[86:89], 0
	global_store_short v[0:1], v2, off
	v_subrev_u32_e32 v0, 62, v80
	v_xad_u32 v1, v102, -3, v166
	v_mfma_f32_16x16x32_f16 v[82:85], v[94:97], v[90:93], v[82:85]
	v_cndmask_b32_e64 v36, v1, v0, s[2:3]
	v_add_u32_e32 v36, v36, v173
	s_nop 0
	s_waitcnt lgkmcnt(1)
	v_mfma_f32_16x16x32_f16 v[68:71], v[76:79], v[68:71], 0
	v_mfma_f32_16x16x32_f16 v[86:89], v[76:79], v[86:89], 0
	s_nop 2
	v_cvt_f16_f32_e32 v1, v82
	v_cvt_f16_f32_e32 v2, v83
	v_cvt_f16_f32_e32 v66, v85
	v_mfma_f32_16x16x32_f16 v[72:75], v[90:93], v[94:97], v[72:75]
	v_mov_b32_e32 v85, v3
	v_cndmask_b32_e64 v66, 0, v66, s[22:23]
	s_nop 0
	s_waitcnt lgkmcnt(0)
	v_mfma_f32_16x16x32_f16 v[76:79], v[90:93], v[128:131], v[62:65]
	v_mov_b32_e32 v92, v3
	s_nop 2
	v_cndmask_b32_e64 v0, 0, v72, s[10:11]
	v_cndmask_b32_e64 v37, 0, v73, s[14:15]
	v_cvt_f16_f32_e32 v63, v84
	v_mfma_f32_16x16x32_f16 v[94:97], v[98:101], v[94:97], v[68:71]
	v_cndmask_b32_e64 v64, 0, v74, s[16:17]
	v_cndmask_b32_e64 v65, 0, v75, s[20:21]
	v_cndmask_b32_e64 v63, 0, v63, s[18:19]
	v_cndmask_b32_e64 v68, 0, v1, s[12:13]
	v_cndmask_b32_e64 v69, v2, 0, s[10:11]
	v_add_f32_e32 v62, v215, v0
	v_cvt_pk_f16_f32 v1, v64, v65
	v_cvt_pk_f16_f32 v0, v0, v37
	v_mov_b32_e32 v2, v3
	v_pack_b32_f16 v67, v63, v66
	v_pack_b32_f16 v66, v68, v69
	v_mov_b32_e32 v68, v3
	v_mov_b32_e32 v69, v3
	v_add_f32_e32 v63, v217, v37
	v_add_f32_e32 v64, v218, v64
	v_mfma_f32_16x16x32_f16 v[70:73], v[0:3], v[66:69], 0
	v_add_f32_e32 v65, v219, v65
	v_cvt_pk_f16_f32 v83, v64, v65
	v_cvt_pk_f16_f32 v82, v62, v63
	v_mfma_f32_16x16x32_f16 v[66:69], v[66:69], v[0:3], 0
	v_mov_b32_e32 v84, v3
	s_nop 2
	v_cvt_pk_f16_f32 v0, v70, v71
	v_mov_b32_e32 v70, v3
	v_mov_b32_e32 v71, v3
	v_cvt_pk_f16_f32 v1, v72, v73
	v_cvt_pk_f16_f32 v69, v68, v69
	v_cvt_pk_f16_f32 v68, v66, v67
	v_mfma_f32_16x16x32_f16 v[62:65], v[0:3], v[82:85], v[62:65]
	v_mad_i64_i32 v[36:37], s[28:29], v36, s91, v[126:127]
	global_store_short v[36:37], v60, off
	v_mfma_f32_16x16x32_f16 v[72:75], v[68:71], v[0:3], 0
	v_cvt_f16_f32_e32 v82, v61
	v_subrev_u32_e32 v36, 61, v80
	v_xad_u32 v37, v102, -4, v166
	v_mfma_f32_16x16x32_f16 v[66:69], v[0:3], v[68:71], 0
	s_nop 0
	v_cvt_pk_f16_f32 v71, v64, v65
	s_nop 1
	v_cvt_pk_f16_f32 v1, v74, v75
	v_cvt_pk_f16_f32 v0, v72, v73
	ds_read2_b64 v[136:139], v227 offset1:4
	v_mfma_f32_16x16x32_f16 v[56:59], v[98:101], v[128:131], v[86:89]
	v_cvt_pk_f16_f32 v70, v62, v63
	v_mov_b32_e32 v72, v3
	v_mov_b32_e32 v73, v3
	v_cvt_pk_f16_f32 v85, v68, v69
	ds_read2_b64 v[128:131], v227 offset0:8 offset1:12
	v_cvt_pk_f16_f32 v84, v66, v67
	v_mov_b32_e32 v86, v3
	v_mov_b32_e32 v87, v3
	v_mfma_f32_16x16x32_f16 v[88:91], v[0:3], v[70:73], v[62:65]
	s_nop 0
	s_nop 0
	v_cndmask_b32_e64 v36, v37, v36, s[2:3]
	v_mfma_f32_16x16x32_f16 v[60:63], v[84:87], v[0:3], 0
	v_add_u32_e32 v83, v36, v173
	s_nop 2
	v_cvt_pk_f16_f32 v1, v90, v91
	v_cvt_pk_f16_f32 v0, v88, v89
	v_cvt_pk_f16_f32 v67, v54, v55
	v_cvt_pk_f16_f32 v66, v52, v53
	v_cvt_pk_f16_f32 v85, v62, v63
	v_cvt_pk_f16_f32 v84, v60, v61
	v_cvt_pk_f16_f32 v63, v50, v51
	v_cvt_pk_f16_f32 v62, v48, v49
	v_cvt_pk_f16_f32 v61, v42, v43
	v_cvt_pk_f16_f32 v60, v40, v41
	v_cvt_pk_f16_f32 v65, v46, v47
	v_cvt_pk_f16_f32 v64, v44, v45
	s_nop 0
	s_waitcnt lgkmcnt(1)
	v_mfma_f32_16x16x32_f16 v[68:71], v[136:139], v[60:63], 0
	v_add_u32_e32 v36, 0x1000, v227
	v_mov_b32_e32 v93, v3
	v_cvt_f16_f32_e32 v76, v76
	s_nop 0
	s_waitcnt lgkmcnt(0)
	v_mfma_f32_16x16x32_f16 v[98:101], v[128:131], v[64:67], v[68:71]
	ds_read2_b64 v[72:75], v36 offset0:64 offset1:68
	s_nop 1
	ds_read2_b64 v[68:71], v36 offset0:72 offset1:76
	v_cvt_f16_f32_e32 v36, v97
	v_cvt_f16_f32_e32 v97, v77
	v_mfma_f32_16x16x32_f16 v[84:87], v[84:87], v[0:3], v[88:91]
	v_cvt_f16_f32_e32 v0, v94
	v_cvt_f16_f32_e32 v1, v95
	v_cvt_f16_f32_e32 v2, v96
	v_cndmask_b32_e64 v96, v76, 0, s[12:13]
	v_cndmask_b32_e64 v0, 0, v0, s[10:11]
	v_cndmask_b32_e64 v37, 0, v1, s[14:15]
	v_cndmask_b32_e64 v1, 0, v2, s[16:17]
	v_cndmask_b32_e64 v2, 0, v36, s[20:21]
	v_pack_b32_f16 v1, v1, v2
	v_pack_b32_f16 v0, v0, v37
	v_mov_b32_e32 v2, v3
	v_mov_b32_e32 v36, v134
	v_mov_b32_e32 v37, v135
	v_mov_b32_e32 v38, v3
	v_mov_b32_e32 v39, v3
	v_mov_b32_e32 v94, v3
	v_mov_b32_e32 v95, v3
	v_mfma_f32_16x16x32_f16 v[88:91], v[0:3], v[36:39], v[98:101]
	v_cvt_pk_f16_f32 v1, v86, v87
	v_cvt_pk_f16_f32 v0, v84, v85
	v_cvt_f16_f32_e32 v56, v56
	v_cvt_f16_f32_e32 v98, v78
	v_cvt_f16_f32_e32 v99, v79
	s_nop 2
	v_cvt_pk_f16_f32 v91, v90, v91
	v_cvt_pk_f16_f32 v90, v88, v89
	v_cndmask_b32_e64 v97, 0, v97, s[10:11]
	v_cndmask_b32_e64 v98, v98, 0, s[18:19]
	v_mfma_f32_16x16x32_f16 v[84:87], v[0:3], v[90:93], 0
	v_add_u32_e32 v2, 0x800, v236
	ds_read2_b64 v[128:131], v2 offset0:64 offset1:144
	ds_read_b128 v[76:79], v180 offset:256
	v_mov_b32_e32 v90, v3
	v_mov_b32_e32 v91, v3
	v_cndmask_b32_e64 v99, v99, 0, s[22:23]
	ds_read_b64 v[88:89], v228 offset:5120
	ds_read_b128 v[132:135], v180 offset:320
	s_nop 3
	v_cvt_pk_f16_f32 v1, v86, v87
	v_cvt_pk_f16_f32 v0, v84, v85
	s_nop 0
	s_nop 0
	s_nop 0
	v_mov_b32_e32 v2, v3
	s_nop 0
	s_waitcnt lgkmcnt(3)
	v_mov_b32_e32 v92, v128
	v_mov_b32_e32 v93, v129
	ds_read_b64 v[84:85], v229 offset:5120
	s_nop 0
	s_waitcnt lgkmcnt(3)
	v_pk_mul_f32 v[42:43], v[42:43], v[78:79]
	v_pk_mul_f32 v[40:41], v[40:41], v[76:77]
	s_nop 0
	s_nop 0
	v_mfma_f32_16x16x32_f16 v[40:43], v[92:95], v[0:3], v[40:43]
	s_nop 0
	s_waitcnt lgkmcnt(1)
	v_pk_mul_f32 v[48:49], v[48:49], v[132:133]
	v_add_u32_e32 v76, 0xc00, v236
	ds_read2_b64 v[136:139], v230 offset1:80
	ds_read_b128 v[140:143], v180 offset:384
	v_mfma_f32_16x16x32_f16 v[40:43], v[88:91], v[36:39], v[40:43]
	v_mov_b32_e32 v88, v130
	v_mov_b32_e32 v89, v131
	v_pk_mul_f32 v[50:51], v[50:51], v[134:135]
	v_mov_b32_e32 v86, v3
	v_mov_b32_e32 v87, v3
	s_nop 0
	v_mfma_f32_16x16x32_f16 v[48:51], v[88:91], v[0:3], v[48:51]
	ds_read_b64 v[88:89], v230 offset:5120
	s_nop 0
	s_waitcnt lgkmcnt(2)
	v_mov_b32_e32 v92, v136
	v_mfma_f32_16x16x32_f16 v[48:51], v[84:87], v[36:39], v[48:51]
	s_nop 0
	s_nop 0
	v_mov_b32_e32 v93, v137
	v_pack_b32_f16 v76, v96, v97
	v_cndmask_b32_e64 v96, v56, 0, s[12:13]
	s_nop 0
	s_waitcnt lgkmcnt(1)
	v_pk_mul_f32 v[46:47], v[46:47], v[142:143]
	v_pk_mul_f32 v[44:45], v[44:45], v[140:141]
	ds_read_b128 v[84:87], v180 offset:448
	v_cvt_f16_f32_e32 v56, v57
	v_cvt_f16_f32_e32 v57, v58
	v_mfma_f32_16x16x32_f16 v[44:47], v[92:95], v[0:3], v[44:47]
	v_cvt_f16_f32_e32 v58, v59
	v_mov_b32_e32 v92, v138
	v_mov_b32_e32 v93, v139
	s_nop 0
	s_waitcnt lgkmcnt(1)
	v_mfma_f32_16x16x32_f16 v[44:47], v[88:91], v[36:39], v[44:47]
	ds_read_b64 v[88:89], v231 offset:5120
	s_nop 0
	s_nop 0
	v_cndmask_b32_e64 v78, v57, 0, s[18:19]
	v_cndmask_b32_e64 v79, v58, 0, s[22:23]
	v_pack_b32_f16 v77, v98, v99
	s_nop 0
	s_waitcnt lgkmcnt(1)
	v_pk_mul_f32 v[52:53], v[52:53], v[84:85]
	v_cndmask_b32_e64 v84, 0, v56, s[10:11]
	v_mfma_f32_16x16x32_f16 v[56:59], v[72:75], v[60:63], 0
	v_pack_b32_f16 v61, v78, v79
	v_mov_b32_e32 v78, v3
	v_mov_b32_e32 v79, v3
	v_mfma_f32_16x16x32_f16 v[56:59], v[68:71], v[64:67], v[56:59]
	v_mul_f32_e64 v54, v54, v86
	v_mul_f32_e64 v55, v55, v87
	v_pack_b32_f16 v60, v96, v84
	v_mov_b32_e32 v62, v3
	v_mov_b32_e32 v63, v3
	v_mfma_f32_16x16x32_f16 v[52:55], v[92:95], v[0:3], v[52:55]
	v_mfma_f32_16x16x32_f16 v[56:59], v[76:79], v[0:3], v[56:59]
	v_mad_i64_i32 v[0:1], s[28:29], v83, s91, v[126:127]
	global_store_short v[0:1], v82, off
	s_nop 0
	s_waitcnt lgkmcnt(0)
	v_mfma_f32_16x16x32_f16 v[52:55], v[88:91], v[36:39], v[52:55]
	v_subrev_u32_e32 v0, 48, v80
	v_add_u32_e32 v1, 0xef, v81
	v_cndmask_b32_e64 v0, v1, v0, s[2:3]
	v_mfma_f32_16x16x32_f16 v[36:39], v[60:63], v[36:39], v[56:59]
	v_add_u32_e32 v0, v0, v173
	v_mad_i64_i32 v[0:1], s[28:29], v0, s91, v[126:127]
	s_nop 5
	v_cvt_f16_f32_e32 v2, v36
	global_store_short v[0:1], v2, off
	v_subrev_u32_e32 v0, 47, v80
	v_add_u32_e32 v1, 0xee, v81
	v_cvt_f16_f32_e32 v2, v37
	v_cndmask_b32_e64 v0, v1, v0, s[2:3]
	v_add_u32_e32 v0, v0, v173
	v_mad_i64_i32 v[0:1], s[28:29], v0, s91, v[126:127]
	global_store_short v[0:1], v2, off
	v_subrev_u32_e32 v0, 46, v80
	v_add_u32_e32 v1, 0xed, v81
	v_cvt_f16_f32_e32 v2, v38
	v_cndmask_b32_e64 v0, v1, v0, s[2:3]
	v_add_u32_e32 v0, v0, v173
	v_mad_i64_i32 v[0:1], s[28:29], v0, s91, v[126:127]
	global_store_short v[0:1], v2, off
	v_subrev_u32_e32 v0, 45, v80
	v_add_u32_e32 v1, 0xec, v81
	v_cndmask_b32_e64 v0, v1, v0, s[2:3]
	v_cvt_f16_f32_e32 v2, v39
	v_add_u32_e32 v0, v0, v173
	v_mad_i64_i32 v[0:1], s[28:29], v0, s91, v[126:127]
	s_mov_b64 s[28:29], 0
	global_store_short v[0:1], v2, off

.LBB0_452:
	v_mov_b32_e32 v2, s47
	v_mov_b32_e32 v37, s45
	v_cndmask_b32_e64 v43, v2, v37, s[2:3]
	v_mov_b32_e32 v2, s46
	v_mov_b32_e32 v37, s44
	v_cndmask_b32_e64 v42, v2, v37, s[2:3]
	v_lshlrev_b32_e32 v2, 1, v76
	v_bfe_u32 v44, v76, 5, 1
	v_and_b32_e32 v45, 62, v2
	v_lshl_or_b32 v2, v44, 6, v45
	v_readlane_b32 s6, v255, 38
	v_lshlrev_b32_e32 v46, 2, v45
	v_readlane_b32 s7, v255, 39
	v_mad_u32_u24 v174, v2, 40, s6
	v_lshlrev_b32_e32 v2, 8, v44
	s_waitcnt vmcnt(0)
	v_lshlrev_b32_e32 v47, 1, v153
	v_add3_u32 v175, s7, v2, v46
	v_lshl_add_u32 v176, v153, 2, s7
	v_add_u32_e32 v48, s6, v47
	v_readlane_b32 s6, v255, 28
	v_ashrrev_i32_e32 v37, 31, v36
	v_readlane_b32 s7, v255, 29
	v_lshl_add_u64 v[42:43], v[36:37], 1, v[42:43]
	s_lshl_b32 s6, s8, 1
	s_mov_b32 s9, s7
	v_writelane_b32 v255, s8, 28
	v_lshl_add_u64 v[42:43], v[42:43], 0, s[6:7]
	v_lshlrev_b32_e32 v2, 1, v74
	v_writelane_b32 v255, s9, 29
	v_lshl_add_u64 v[122:123], v[42:43], 0, v[2:3]
	v_lshlrev_b32_e32 v2, 1, v120
	v_lshlrev_b32_e32 v42, 1, v40
	v_add3_u32 v177, 0, v2, v42
	v_lshl_add_u64 v[124:125], v[0:1], 2, v[58:59]
	v_mul_u32_u24_e32 v0, 0x900, v44
	v_lshlrev_b32_e32 v2, 1, v45
	v_readlane_b32 s26, v255, 40
	v_lshlrev_b32_e32 v1, 1, v38
	v_cmp_eq_u32_e32 vcc, v153, v74
	v_add3_u32 v179, s26, v0, v2
	v_lshl_or_b32 v0, v44, 4, 1
	v_or_b32_e32 v38, 1, v153
	v_lshlrev_b32_e32 v180, 6, v0
	v_mul_u32_u24_e32 v0, 0x90, v0
	v_cndmask_b32_e64 v211, 0, 1.0, vcc
	v_cmp_lt_u32_e64 s[14:15], v38, v74
	v_cmp_eq_u32_e32 vcc, v38, v74
	v_or_b32_e32 v38, 2, v153
	v_add3_u32 v181, s26, v0, v2
	v_add_u32_e32 v0, s26, v42
	v_cndmask_b32_e64 v212, 0, 1.0, vcc
	v_cmp_lt_u32_e64 s[16:17], v38, v74
	v_cmp_lt_u32_e64 s[18:19], v74, v38
	v_cmp_eq_u32_e32 vcc, v38, v74
	v_or_b32_e32 v38, 3, v153
	v_add_u32_e32 v210, v0, v1
	v_cndmask_b32_e64 v213, 0, 1.0, vcc
	v_cmp_lt_u32_e64 s[20:21], v38, v74
	v_cmp_lt_u32_e64 s[22:23], v74, v38
	v_cmp_eq_u32_e32 vcc, v38, v74
	v_add_u32_e32 v215, v0, v47
	v_or_b32_e32 v0, 16, v74
	v_mov_b32_e32 v38, s26
	v_or3_b32 v36, v36, v39, v153
	v_mad_u32_u24 v0, v0, s92, v38
	v_ashrrev_i32_e32 v37, 31, v36
	v_add_u32_e32 v221, v0, v1
	v_add_u32_e32 v222, v0, v47
	v_lshlrev_b32_e32 v0, 12, v44
	v_readlane_b32 s36, v254, 53
	v_or_b32_e32 v40, 16, v36
	v_add3_u32 v227, 0, v46, v0
	v_lshlrev_b64 v[0:1], 2, v[56:57]
	v_readlane_b32 s37, v254, 54
	v_readlane_b32 s38, v254, 55
	v_readlane_b32 s39, v254, 56
	v_readlane_b32 s40, v254, 57
	v_readlane_b32 s41, v254, 58
	v_readlane_b32 s42, v254, 59
	v_readlane_b32 s43, v254, 60
	v_readlane_b32 s44, v254, 61
	v_readlane_b32 s45, v254, 62
	v_readlane_b32 s46, v254, 63
	v_readlane_b32 s47, v255, 0
	v_readlane_b32 s48, v255, 1
	v_readlane_b32 s49, v255, 2
	v_readlane_b32 s50, v255, 3
	v_readlane_b32 s51, v255, 4
	v_lshlrev_b64 v[42:43], 2, v[36:37]
	v_bfe_u32 v172, v76, 6, 2
	v_lshlrev_b32_e32 v173, 10, v44
	v_ashrrev_i32_e32 v41, 31, v40
	v_mul_u32_u24_e32 v45, 40, v74
	v_mad_u32_u24 v217, v74, 40, v48
	v_lshl_add_u64 v[38:39], s[38:39], 0, v[0:1]
	v_lshl_add_u64 v[0:1], s[42:43], 0, v[0:1]
	v_lshl_add_u64 v[130:131], s[46:47], 0, v[42:43]
	v_lshl_add_u64 v[132:133], s[48:49], 0, v[42:43]
	v_lshl_add_u64 v[134:135], s[50:51], 0, v[42:43]
	s_mov_b64 s[36:37], s[52:53]
	s_mov_b32 s70, 0
	v_cmp_eq_u32_e64 s[4:5], 0, v172
	v_add_u32_e32 v178, 0xe000, v177
	v_cmp_gt_u32_e64 s[6:7], 8, v74
	v_cmp_eq_u32_e64 s[8:9], v78, v79
	v_or_b32_e32 v182, 0x80, v173
	v_add_u32_e32 v183, 0x90, v181
	v_or_b32_e32 v184, 0xc0, v173
	v_add_u32_e32 v185, 0x120, v181
	v_or_b32_e32 v186, 0x100, v173
	v_add_u32_e32 v187, 0x1b0, v181
	v_or_b32_e32 v188, 0x140, v173
	v_add_u32_e32 v189, 0x240, v181
	v_or_b32_e32 v190, 0x180, v173
	v_add_u32_e32 v191, 0x2d0, v181
	v_or_b32_e32 v192, 0x1c0, v173
	v_add_u32_e32 v193, 0x360, v181
	v_or_b32_e32 v194, 0x200, v173
	v_add_u32_e32 v195, 0x3f0, v181
	v_or_b32_e32 v196, 0x240, v173
	v_add_u32_e32 v197, 0x480, v181
	v_or_b32_e32 v198, 0x280, v173
	v_add_u32_e32 v199, 0x510, v181
	v_or_b32_e32 v200, 0x2c0, v173
	v_add_u32_e32 v201, 0x5a0, v181
	v_or_b32_e32 v202, 0x300, v173
	v_add_u32_e32 v203, 0x630, v181
	v_or_b32_e32 v204, 0x340, v173
	v_add_u32_e32 v205, 0x6c0, v181
	v_or_b32_e32 v206, 0x380, v173
	v_add_u32_e32 v207, 0x750, v181
	v_or_b32_e32 v208, 0x3c0, v173
	v_add_u32_e32 v209, 0x7e0, v181
	v_and_b32_e32 v244, 31, v238
	v_lshlrev_b32_e32 v244, 1, v244
	v_xor_b32_e32 v245, 4, v244
	v_sub_u32_e32 v245, v245, v244
	v_xor_b32_e32 v246, 8, v244
	v_sub_u32_e32 v246, v246, v244
	v_xor_b32_e32 v247, 12, v244
	v_sub_u32_e32 v247, v247, v244
	v_add_u32_e32 v182, v182, v245
	v_add_u32_e32 v184, v184, v245
	v_add_u32_e32 v186, v186, v246
	v_add_u32_e32 v188, v188, v246
	v_add_u32_e32 v190, v190, v247
	v_add_u32_e32 v192, v192, v247
	v_add_u32_e32 v198, v198, v245
	v_add_u32_e32 v200, v200, v245
	v_add_u32_e32 v202, v202, v246
	v_add_u32_e32 v204, v204, v246
	v_add_u32_e32 v206, v206, v247
	v_add_u32_e32 v208, v208, v247
	v_cmp_lt_u32_e64 s[10:11], v153, v74
	v_cmp_lt_u32_e64 s[12:13], v74, v153
	v_cndmask_b32_e64 v214, 0, 1.0, vcc
	v_mad_u32_u24 v216, v75, 40, v48
	v_add_u32_e32 v218, 0x280, v217
	v_add_u32_e32 v219, 0x500, v217
	v_add_u32_e32 v220, 0x780, v217
	v_add_u32_e32 v223, 0xa00, v217
	v_add_u32_e32 v224, 0xc80, v217
	v_add_u32_e32 v225, 0xf00, v217
	v_add_u32_e32 v226, 0x1180, v217
	v_bfe_u32 v244, v238, 4, 2
	v_xor_b32_e32 v245, 1, v244
	v_sub_u32_e32 v245, v245, v244
	v_lshlrev_b32_e32 v245, 3, v245
	v_add_u32_e32 v219, v219, v245
	v_add_u32_e32 v220, v220, v245
	v_add_u32_e32 v225, v225, v245
	v_add_u32_e32 v226, v226, v245
	v_bfe_u32 v246, v238, 7, 1
	v_xor_b32_e32 v247, v244, v246
	v_sub_u32_e32 v247, v247, v244
	v_lshlrev_b32_e32 v247, 3, v247
	v_add_u32_e32 v216, v216, v247
	v_bfe_u32 v246, v238, 4, 1
	v_bfe_u32 v247, v238, 6, 2
	v_xor_b32_e32 v246, v247, v246
	v_sub_u32_e32 v246, v246, v247
	v_lshlrev_b32_e32 v246, 3, v246
	v_add_u32_e32 v174, v174, v246
	v_lshl_add_u64 v[126:127], v[38:39], 0, v[42:43]
	v_lshl_add_u64 v[128:129], v[0:1], 0, v[42:43]
	v_add_u32_e32 v228, 0, v2
	v_sub_u32_e32 v229, 0x7df, v150
	v_sub_u32_e32 v230, 0, v77
	s_mov_b32 s71, 64
	v_add_u32_e32 v231, v48, v45
	v_lshlrev_b64 v[136:137], 1, v[36:37]
	v_lshlrev_b64 v[138:139], 1, v[40:41]
	s_mov_b32 s76, 0
	s_mov_b64 s[38:39], s[54:55]
	s_mov_b64 s[40:41], s[56:57]
	s_mov_b64 s[42:43], s[58:59]
	s_mov_b64 s[44:45], s[60:61]
	s_mov_b64 s[46:47], s[62:63]
	s_mov_b64 s[48:49], s[64:65]
	s_mov_b64 s[50:51], s[66:67]
	s_waitcnt lgkmcnt(0)
	s_barrier
	s_branch .LBB0_455

.LBB0_462:
	s_or_b64 exec, exec, s[26:27]
	s_waitcnt lgkmcnt(0)
	s_barrier
	ds_read_b128 v[40:43], v210 offset:9216
	ds_read_b128 v[48:51], v210 offset:18496
	ds_read_b128 v[56:59], v210 offset:9280
	ds_read_b128 v[60:63], v210 offset:23040
	ds_read_b128 v[36:39], v210 offset:18432
	s_nop 0
	s_nop 0
	s_nop 0
	ds_read_b128 v[64:67], v210 offset:13824
	s_waitcnt lgkmcnt(1)
	v_mfma_f32_16x16x32_f16 v[52:55], v[40:43], v[36:39], 0
	s_nop 0
	s_nop 0
	s_nop 0
	ds_read_b128 v[68:71], v210 offset:13888
	ds_read_b128 v[72:75], v210 offset:23104
	v_add_u32_e32 v80, 0x1000, v215
	s_nop 0
	v_mfma_f32_16x16x32_f16 v[52:55], v[56:59], v[48:51], v[52:55]
	v_mov_b32_e32 v82, v3
	v_mov_b32_e32 v83, v3
	v_mov_b32_e32 v86, v3
	v_mfma_f32_16x16x32_f16 v[44:47], v[36:39], v[40:43], 0
	s_nop 3
	v_cvt_f16_f32_e32 v0, v52
	v_cvt_f16_f32_e32 v1, v54
	v_cvt_f16_f32_e32 v2, v55
	v_mfma_f32_16x16x32_f16 v[44:47], v[48:51], v[56:59], v[44:47]
	v_cndmask_b32_e64 v79, 0, v0, s[12:13]
	v_cvt_f16_f32_e32 v0, v53
	v_cndmask_b32_e64 v54, 0, v1, s[18:19]
	s_nop 0
	v_mfma_f32_16x16x32_f16 v[40:43], v[60:63], v[40:43], 0
	v_cndmask_b32_e64 v55, 0, v2, s[22:23]
	s_nop 1
	v_cndmask_b32_e64 v76, 0, v44, s[10:11]
	v_cndmask_b32_e64 v77, 0, v45, s[14:15]
	s_nop 0
	s_waitcnt lgkmcnt(2)
	v_mfma_f32_16x16x32_f16 v[36:39], v[36:39], v[64:67], 0
	v_cndmask_b32_e64 v52, 0, v46, s[16:17]
	v_cndmask_b32_e64 v78, 0, v47, s[20:21]
	v_cndmask_b32_e64 v53, v0, 0, s[10:11]
	v_mfma_f32_16x16x32_f16 v[44:47], v[60:63], v[64:67], 0
	v_cvt_pk_f16_f32 v1, v52, v78
	v_cvt_pk_f16_f32 v0, v76, v77
	v_mov_b32_e32 v2, v3
	s_nop 0
	s_waitcnt lgkmcnt(0)
	v_mfma_f32_16x16x32_f16 v[60:63], v[72:75], v[56:59], v[40:43]
	v_add_f32_e32 v56, v211, v76
	v_add_f32_e32 v57, v212, v77
	v_add_f32_e32 v58, v213, v52
	v_mfma_f32_16x16x32_f16 v[40:43], v[48:51], v[68:71], v[36:39]
	v_add_f32_e32 v59, v214, v78
	v_cvt_pk_f16_f32 v67, v18, v19
	v_cvt_pk_f16_f32 v66, v16, v17
	v_pack_b32_f16 v37, v54, v55
	v_pack_b32_f16 v36, v79, v53
	v_mov_b32_e32 v38, v3
	v_mov_b32_e32 v39, v3
	v_mfma_f32_16x16x32_f16 v[52:55], v[72:75], v[68:71], v[44:47]
	ds_read2_b64 v[68:71], v215 offset0:8 offset1:12
	v_cvt_pk_f16_f32 v65, v14, v15
	v_cvt_pk_f16_f32 v64, v12, v13
	v_mfma_f32_16x16x32_f16 v[48:51], v[0:3], v[36:39], 0
	v_cvt_pk_f16_f32 v45, v58, v59
	v_cvt_pk_f16_f32 v44, v56, v57
	v_mov_b32_e32 v46, v3
	v_mfma_f32_16x16x32_f16 v[36:39], v[36:39], v[0:3], 0
	v_mov_b32_e32 v47, v3
	s_nop 2
	v_cvt_pk_f16_f32 v1, v50, v51
	v_cvt_pk_f16_f32 v0, v48, v49
	v_mov_b32_e32 v50, v3
	v_mov_b32_e32 v51, v3
	v_cvt_pk_f16_f32 v49, v38, v39
	v_cvt_pk_f16_f32 v48, v36, v37
	v_mfma_f32_16x16x32_f16 v[44:47], v[0:3], v[44:47], v[56:59]
	v_mov_b32_e32 v87, v3
	v_mov_b32_e32 v90, v3
	v_mov_b32_e32 v91, v3
	v_mfma_f32_16x16x32_f16 v[36:39], v[48:51], v[0:3], 0
	ds_read2_b64 v[126:129], v215 offset1:4
	v_cvt_pk_f16_f32 v59, v10, v11
	v_cvt_pk_f16_f32 v58, v8, v9
	v_cvt_pk_f16_f32 v57, v6, v7
	v_mfma_f32_16x16x32_f16 v[48:51], v[0:3], v[48:51], 0
	v_cvt_pk_f16_f32 v56, v4, v5
	s_nop 2
	v_cvt_pk_f16_f32 v1, v38, v39
	v_cvt_pk_f16_f32 v0, v36, v37
	v_cvt_pk_f16_f32 v37, v46, v47
	v_cvt_pk_f16_f32 v36, v44, v45
	v_mov_b32_e32 v38, v3
	v_mov_b32_e32 v39, v3
	v_cvt_f16_f32_e32 v52, v52
	s_add_i32 s28, s76, 1
	v_mfma_f32_16x16x32_f16 v[44:47], v[0:3], v[36:39], v[44:47]
	v_cvt_pk_f16_f32 v37, v50, v51
	v_cvt_pk_f16_f32 v36, v48, v49
	v_mov_b32_e32 v50, v3
	v_mov_b32_e32 v51, v3
	v_mfma_f32_16x16x32_f16 v[36:39], v[36:39], v[0:3], 0
	s_nop 2
	v_cvt_pk_f16_f32 v1, v46, v47
	v_cvt_pk_f16_f32 v0, v44, v45
	s_nop 2
	v_cvt_pk_f16_f32 v49, v38, v39
	v_cvt_pk_f16_f32 v48, v36, v37
	s_nop 0
	s_nop 0
	s_waitcnt lgkmcnt(0)
	v_mfma_f32_16x16x32_f16 v[36:39], v[126:129], v[56:59], 0
	v_mfma_f32_16x16x32_f16 v[44:47], v[48:51], v[0:3], v[44:47]
	v_cvt_f16_f32_e32 v0, v60
	v_cvt_f16_f32_e32 v1, v61
	v_cvt_f16_f32_e32 v2, v62
	v_cvt_f16_f32_e32 v48, v63
	v_mfma_f32_16x16x32_f16 v[76:79], v[68:71], v[64:67], v[36:39]
	ds_read2_b64 v[72:75], v80 offset0:64 offset1:68
	ds_read2st64_b64 v[130:133], v216 offset0:20 offset1:25
	ds_read2_b64 v[68:71], v80 offset0:72 offset1:76
	s_nop 0
	s_nop 0
	v_cndmask_b32_e64 v0, 0, v0, s[10:11]
	v_cndmask_b32_e64 v49, 0, v1, s[14:15]
	v_cndmask_b32_e64 v1, 0, v2, s[16:17]
	v_cndmask_b32_e64 v2, 0, v48, s[20:21]
	v_pack_b32_f16 v1, v1, v2
	v_pack_b32_f16 v0, v0, v49
	v_mov_b32_e32 v2, v3
	s_nop 0
	s_waitcnt lgkmcnt(1)
	v_mov_b32_e32 v60, v130
	v_mov_b32_e32 v61, v131
	ds_read2_b64 v[126:129], v231 offset1:80
	v_mov_b32_e32 v62, v3
	v_mov_b32_e32 v63, v3
	v_cvt_f16_f32_e32 v36, v40
	ds_read_b128 v[134:137], v176
	v_cvt_f16_f32_e32 v40, v42
	v_mfma_f32_16x16x32_f16 v[48:51], v[0:3], v[60:63], v[76:79]
	v_cvt_pk_f16_f32 v1, v46, v47
	v_cvt_pk_f16_f32 v0, v44, v45
	v_cvt_f16_f32_e32 v37, v41
	v_mov_b32_e32 v78, v3
	v_mov_b32_e32 v79, v3
	s_nop 2
	v_cvt_pk_f16_f32 v77, v50, v51
	v_cvt_pk_f16_f32 v76, v48, v49
	v_cndmask_b32_e64 v88, v40, 0, s[18:19]
	v_mfma_f32_16x16x32_f16 v[56:59], v[72:75], v[56:59], 0
	v_cndmask_b32_e64 v36, v36, 0, s[12:13]
	v_cndmask_b32_e64 v37, 0, v37, s[10:11]
	v_mov_b32_e32 v74, v3
	v_mfma_f32_16x16x32_f16 v[44:47], v[0:3], v[76:79], 0
	ds_read_b64 v[76:77], v217 offset:5120
	ds_read_b128 v[138:141], v176 offset:64
	v_mov_b32_e32 v75, v3
	s_waitcnt lgkmcnt(4)
	v_mfma_f32_16x16x32_f16 v[56:59], v[68:71], v[64:67], v[56:59]
	s_nop 5
	v_cvt_pk_f16_f32 v1, v46, v47
	v_cvt_pk_f16_f32 v0, v44, v45
	s_nop 0
	s_nop 0
	s_nop 0
	s_nop 0
	s_waitcnt lgkmcnt(3)
	v_mov_b32_e32 v80, v126
	v_mov_b32_e32 v81, v127
	ds_read_b64 v[44:45], v218 offset:5120
	ds_read2_b64 v[142:145], v219 offset1:80
	s_nop 0
	s_waitcnt lgkmcnt(4)
	v_pk_mul_f32 v[50:51], v[6:7], v[136:137]
	v_pk_mul_f32 v[48:49], v[4:5], v[134:135]
	ds_read_b128 v[134:137], v176 offset:128
	s_nop 1
	v_mfma_f32_16x16x32_f16 v[48:51], v[80:83], v[0:3], v[48:51]
	v_cvt_f16_f32_e32 v80, v43
	v_cndmask_b32_e64 v89, v80, 0, s[22:23]
	s_nop 0
	s_waitcnt lgkmcnt(4)
	v_mfma_f32_16x16x32_f16 v[40:43], v[76:79], v[60:63], v[48:51]
	s_nop 3
	s_nop 0
	s_nop 0
	ds_read_b64 v[80:81], v219 offset:5120
	v_mov_b32_e32 v76, v128
	v_mov_b32_e32 v77, v129
	v_mov_b32_e32 v46, v3
	s_nop 0
	s_waitcnt lgkmcnt(4)
	v_pk_mul_f32 v[50:51], v[10:11], v[140:141]
	v_pk_mul_f32 v[48:49], v[8:9], v[138:139]
	v_mov_b32_e32 v47, v3
	ds_read_b128 v[126:129], v176 offset:192
	s_nop 0
	v_mfma_f32_16x16x32_f16 v[48:51], v[76:79], v[0:3], v[48:51]
	s_nop 0
	s_nop 0
	s_waitcnt lgkmcnt(3)
	v_mov_b32_e32 v84, v142
	v_mfma_f32_16x16x32_f16 v[48:51], v[44:47], v[60:63], v[48:51]
	s_nop 0
	s_nop 0
	v_mov_b32_e32 v85, v143
	v_pack_b32_f16 v77, v88, v89
	v_mov_b32_e32 v88, v144
	s_nop 0
	s_waitcnt lgkmcnt(2)
	v_pk_mul_f32 v[46:47], v[14:15], v[136:137]
	v_pk_mul_f32 v[44:45], v[12:13], v[134:135]
	v_mov_b32_e32 v89, v145
	v_pack_b32_f16 v76, v36, v37
	v_mfma_f32_16x16x32_f16 v[44:47], v[84:87], v[0:3], v[44:47]
	ds_read_b64 v[84:85], v220 offset:5120
	v_cndmask_b32_e64 v36, v52, 0, s[12:13]
	v_cvt_f16_f32_e32 v37, v53
	v_cndmask_b32_e64 v37, 0, v37, s[10:11]
	s_nop 0
	s_waitcnt lgkmcnt(2)
	v_mfma_f32_16x16x32_f16 v[44:47], v[80:83], v[60:63], v[44:47]
	s_nop 0
	s_nop 0
	v_pack_b32_f16 v72, v36, v37
	ds_read_b128 v[68:71], v221 offset:9216
	ds_read_b128 v[94:97], v221 offset:9280
	s_nop 0
	s_waitcnt lgkmcnt(3)
	v_pk_mul_f32 v[82:83], v[18:19], v[128:129]
	ds_read_b128 v[64:67], v221 offset:18432
	v_pk_mul_f32 v[80:81], v[16:17], v[126:127]
	s_nop 0
	ds_read_b128 v[98:101], v221 offset:23104
	v_mfma_f32_16x16x32_f16 v[78:81], v[88:91], v[0:3], v[80:83]
	ds_read_b128 v[90:93], v221 offset:18496
	s_nop 1
	v_cvt_f16_f32_e32 v82, v54
	v_cvt_f16_f32_e32 v83, v55
	s_nop 0
	s_waitcnt lgkmcnt(5)
	v_mfma_f32_16x16x32_f16 v[52:55], v[84:87], v[60:63], v[78:81]
	ds_read_b128 v[86:89], v221 offset:13824
	s_nop 1
	v_cndmask_b32_e64 v78, v82, 0, s[18:19]
	v_cndmask_b32_e64 v79, v83, 0, s[22:23]
	v_pack_b32_f16 v73, v78, v79
	v_mov_b32_e32 v78, v3
	v_mov_b32_e32 v79, v3
	v_add_u32_e32 v80, s71, v153
	v_add_u32_e32 v81, s70, v230
	v_mfma_f32_16x16x32_f16 v[56:59], v[76:79], v[0:3], v[56:59]
	ds_read_b128 v[76:79], v221 offset:23040
	v_subrev_u32_e32 v102, 64, v80
	v_add_u32_e32 v0, 0x7ff, v81
	v_mfma_f32_16x16x32_f16 v[58:61], v[72:75], v[60:63], v[56:59]
	v_cndmask_b32_e64 v0, v0, v102, s[2:3]
	v_add_u32_e32 v0, v0, v151
	v_mad_i64_i32 v[0:1], s[26:27], v0, s91, v[122:123]
	s_nop 0
	s_waitcnt lgkmcnt(4)
	v_mfma_f32_16x16x32_f16 v[82:85], v[68:71], v[64:67], 0
	s_nop 2
	v_cvt_f16_f32_e32 v2, v58
	v_cvt_f16_f32_e32 v60, v60
	ds_read_b128 v[126:129], v221 offset:13888
	global_store_short v[0:1], v2, off
	v_subrev_u32_e32 v0, 63, v80
	v_xad_u32 v1, v102, -2, v170
	v_cvt_f16_f32_e32 v2, v59
	s_nop 0
	v_mfma_f32_16x16x32_f16 v[72:75], v[64:67], v[68:71], 0
	v_cndmask_b32_e64 v0, v1, v0, s[2:3]
	v_add_u32_e32 v0, v0, v151
	v_mad_i64_i32 v[0:1], s[26:27], v0, s91, v[122:123]
	s_nop 0
	s_waitcnt lgkmcnt(2)
	v_mfma_f32_16x16x32_f16 v[62:65], v[64:67], v[86:89], 0
	global_store_short v[0:1], v2, off
	v_subrev_u32_e32 v0, 62, v80
	v_xad_u32 v1, v102, -3, v170
	v_mfma_f32_16x16x32_f16 v[82:85], v[94:97], v[90:93], v[82:85]
	v_cndmask_b32_e64 v36, v1, v0, s[2:3]
	v_add_u32_e32 v36, v36, v151
	s_nop 0
	s_waitcnt lgkmcnt(1)
	v_mfma_f32_16x16x32_f16 v[68:71], v[76:79], v[68:71], 0
	v_mfma_f32_16x16x32_f16 v[86:89], v[76:79], v[86:89], 0
	s_nop 2
	v_cvt_f16_f32_e32 v1, v82
	v_cvt_f16_f32_e32 v2, v83
	v_cvt_f16_f32_e32 v66, v85
	v_mfma_f32_16x16x32_f16 v[72:75], v[90:93], v[94:97], v[72:75]
	v_mov_b32_e32 v85, v3
	v_cndmask_b32_e64 v66, 0, v66, s[22:23]
	s_nop 0
	s_waitcnt lgkmcnt(0)
	v_mfma_f32_16x16x32_f16 v[76:79], v[90:93], v[126:129], v[62:65]
	v_mov_b32_e32 v92, v3
	s_nop 2
	v_cndmask_b32_e64 v0, 0, v72, s[10:11]
	v_cndmask_b32_e64 v37, 0, v73, s[14:15]
	v_cvt_f16_f32_e32 v63, v84
	v_mfma_f32_16x16x32_f16 v[94:97], v[98:101], v[94:97], v[68:71]
	v_cndmask_b32_e64 v64, 0, v74, s[16:17]
	v_cndmask_b32_e64 v65, 0, v75, s[20:21]
	v_cndmask_b32_e64 v63, 0, v63, s[18:19]
	v_cndmask_b32_e64 v68, 0, v1, s[12:13]
	v_cndmask_b32_e64 v69, v2, 0, s[10:11]
	v_add_f32_e32 v62, v211, v0
	v_cvt_pk_f16_f32 v1, v64, v65
	v_cvt_pk_f16_f32 v0, v0, v37
	v_mov_b32_e32 v2, v3
	v_pack_b32_f16 v67, v63, v66
	v_pack_b32_f16 v66, v68, v69
	v_mov_b32_e32 v68, v3
	v_mov_b32_e32 v69, v3
	v_add_f32_e32 v63, v212, v37
	v_add_f32_e32 v64, v213, v64
	v_mfma_f32_16x16x32_f16 v[70:73], v[0:3], v[66:69], 0
	v_add_f32_e32 v65, v214, v65
	v_cvt_pk_f16_f32 v83, v64, v65
	v_cvt_pk_f16_f32 v82, v62, v63
	v_mfma_f32_16x16x32_f16 v[66:69], v[66:69], v[0:3], 0
	v_mov_b32_e32 v84, v3
	s_nop 2
	v_cvt_pk_f16_f32 v0, v70, v71
	v_mov_b32_e32 v70, v3
	v_mov_b32_e32 v71, v3
	v_cvt_pk_f16_f32 v1, v72, v73
	v_cvt_pk_f16_f32 v69, v68, v69
	v_cvt_pk_f16_f32 v68, v66, v67
	v_mfma_f32_16x16x32_f16 v[62:65], v[0:3], v[82:85], v[62:65]
	v_mad_i64_i32 v[36:37], s[26:27], v36, s91, v[122:123]
	global_store_short v[36:37], v60, off
	v_mfma_f32_16x16x32_f16 v[72:75], v[68:71], v[0:3], 0
	v_cvt_f16_f32_e32 v82, v61
	v_subrev_u32_e32 v36, 61, v80
	v_xad_u32 v37, v102, -4, v170
	v_mfma_f32_16x16x32_f16 v[66:69], v[0:3], v[68:71], 0
	s_nop 0
	v_cvt_pk_f16_f32 v71, v64, v65
	s_nop 1
	v_cvt_pk_f16_f32 v1, v74, v75
	v_cvt_pk_f16_f32 v0, v72, v73
	ds_read2_b64 v[134:137], v222 offset1:4
	v_mfma_f32_16x16x32_f16 v[56:59], v[98:101], v[126:129], v[86:89]
	v_cvt_pk_f16_f32 v70, v62, v63
	v_mov_b32_e32 v72, v3
	v_mov_b32_e32 v73, v3
	v_cvt_pk_f16_f32 v85, v68, v69
	ds_read2_b64 v[126:129], v222 offset0:8 offset1:12
	v_cvt_pk_f16_f32 v84, v66, v67
	v_mov_b32_e32 v86, v3
	v_mov_b32_e32 v87, v3
	v_mfma_f32_16x16x32_f16 v[88:91], v[0:3], v[70:73], v[62:65]
	s_nop 0
	s_nop 0
	v_cndmask_b32_e64 v36, v37, v36, s[2:3]
	v_mfma_f32_16x16x32_f16 v[60:63], v[84:87], v[0:3], 0
	v_add_u32_e32 v83, v36, v151
	s_nop 2
	v_cvt_pk_f16_f32 v1, v90, v91
	v_cvt_pk_f16_f32 v0, v88, v89
	v_cvt_pk_f16_f32 v67, v54, v55
	v_cvt_pk_f16_f32 v66, v52, v53
	v_cvt_pk_f16_f32 v85, v62, v63
	v_cvt_pk_f16_f32 v84, v60, v61
	v_cvt_pk_f16_f32 v63, v50, v51
	v_cvt_pk_f16_f32 v62, v48, v49
	v_cvt_pk_f16_f32 v61, v42, v43
	v_cvt_pk_f16_f32 v60, v40, v41
	v_cvt_pk_f16_f32 v65, v46, v47
	v_cvt_pk_f16_f32 v64, v44, v45
	s_nop 0
	s_waitcnt lgkmcnt(1)
	v_mfma_f32_16x16x32_f16 v[68:71], v[134:137], v[60:63], 0
	v_add_u32_e32 v36, 0x1000, v222
	v_mov_b32_e32 v93, v3
	v_cvt_f16_f32_e32 v76, v76
	s_nop 0
	s_waitcnt lgkmcnt(0)
	v_mfma_f32_16x16x32_f16 v[98:101], v[126:129], v[64:67], v[68:71]
	ds_read2_b64 v[72:75], v36 offset0:64 offset1:68
	s_nop 1
	ds_read2_b64 v[68:71], v36 offset0:72 offset1:76
	v_cvt_f16_f32_e32 v36, v97
	v_cvt_f16_f32_e32 v97, v77
	v_mfma_f32_16x16x32_f16 v[84:87], v[84:87], v[0:3], v[88:91]
	v_cvt_f16_f32_e32 v0, v94
	v_cvt_f16_f32_e32 v1, v95
	v_cvt_f16_f32_e32 v2, v96
	v_cndmask_b32_e64 v96, v76, 0, s[12:13]
	v_cndmask_b32_e64 v0, 0, v0, s[10:11]
	v_cndmask_b32_e64 v37, 0, v1, s[14:15]
	v_cndmask_b32_e64 v1, 0, v2, s[16:17]
	v_cndmask_b32_e64 v2, 0, v36, s[20:21]
	v_pack_b32_f16 v1, v1, v2
	v_pack_b32_f16 v0, v0, v37
	v_mov_b32_e32 v2, v3
	v_mov_b32_e32 v36, v132
	v_mov_b32_e32 v37, v133
	v_mov_b32_e32 v38, v3
	v_mov_b32_e32 v39, v3
	v_mov_b32_e32 v94, v3
	v_mov_b32_e32 v95, v3
	v_mfma_f32_16x16x32_f16 v[88:91], v[0:3], v[36:39], v[98:101]
	v_cvt_pk_f16_f32 v1, v86, v87
	v_cvt_pk_f16_f32 v0, v84, v85
	v_cvt_f16_f32_e32 v56, v56
	v_cvt_f16_f32_e32 v98, v78
	v_cvt_f16_f32_e32 v99, v79
	s_nop 2
	v_cvt_pk_f16_f32 v91, v90, v91
	v_cvt_pk_f16_f32 v90, v88, v89
	v_cndmask_b32_e64 v97, 0, v97, s[10:11]
	v_cndmask_b32_e64 v98, v98, 0, s[18:19]
	v_mfma_f32_16x16x32_f16 v[84:87], v[0:3], v[90:93], 0
	v_add_u32_e32 v2, 0x800, v231
	ds_read2_b64 v[126:129], v2 offset0:64 offset1:144
	ds_read_b128 v[76:79], v176 offset:256
	v_mov_b32_e32 v90, v3
	v_mov_b32_e32 v91, v3
	v_cndmask_b32_e64 v99, v99, 0, s[22:23]
	ds_read_b64 v[88:89], v223 offset:5120
	ds_read_b128 v[130:133], v176 offset:320
	s_nop 3
	v_cvt_pk_f16_f32 v1, v86, v87
	v_cvt_pk_f16_f32 v0, v84, v85
	s_nop 0
	s_nop 0
	s_nop 0
	v_mov_b32_e32 v2, v3
	s_nop 0
	s_waitcnt lgkmcnt(3)
	v_mov_b32_e32 v92, v126
	v_mov_b32_e32 v93, v127
	ds_read_b64 v[84:85], v224 offset:5120
	s_nop 0
	s_waitcnt lgkmcnt(3)
	v_pk_mul_f32 v[42:43], v[42:43], v[78:79]
	v_pk_mul_f32 v[40:41], v[40:41], v[76:77]
	s_nop 0
	s_nop 0
	v_mfma_f32_16x16x32_f16 v[40:43], v[92:95], v[0:3], v[40:43]
	s_nop 0
	s_waitcnt lgkmcnt(1)
	v_pk_mul_f32 v[48:49], v[48:49], v[130:131]
	v_add_u32_e32 v76, 0xc00, v231
	ds_read2_b64 v[134:137], v225 offset1:80
	ds_read_b128 v[138:141], v176 offset:384
	v_mfma_f32_16x16x32_f16 v[40:43], v[88:91], v[36:39], v[40:43]
	v_mov_b32_e32 v88, v128
	v_mov_b32_e32 v89, v129
	v_pk_mul_f32 v[50:51], v[50:51], v[132:133]
	v_mov_b32_e32 v86, v3
	v_mov_b32_e32 v87, v3
	s_nop 0
	v_mfma_f32_16x16x32_f16 v[48:51], v[88:91], v[0:3], v[48:51]
	ds_read_b64 v[88:89], v225 offset:5120
	s_nop 0
	s_waitcnt lgkmcnt(2)
	v_mov_b32_e32 v92, v134
	v_mfma_f32_16x16x32_f16 v[48:51], v[84:87], v[36:39], v[48:51]
	s_nop 0
	s_nop 0
	v_mov_b32_e32 v93, v135
	v_pack_b32_f16 v76, v96, v97
	v_cndmask_b32_e64 v96, v56, 0, s[12:13]
	s_nop 0
	s_waitcnt lgkmcnt(1)
	v_pk_mul_f32 v[46:47], v[46:47], v[140:141]
	v_pk_mul_f32 v[44:45], v[44:45], v[138:139]
	ds_read_b128 v[84:87], v176 offset:448
	v_cvt_f16_f32_e32 v56, v57
	v_cvt_f16_f32_e32 v57, v58
	v_mfma_f32_16x16x32_f16 v[44:47], v[92:95], v[0:3], v[44:47]
	v_cvt_f16_f32_e32 v58, v59
	v_mov_b32_e32 v92, v136
	v_mov_b32_e32 v93, v137
	s_nop 0
	s_waitcnt lgkmcnt(1)
	v_mfma_f32_16x16x32_f16 v[44:47], v[88:91], v[36:39], v[44:47]
	ds_read_b64 v[88:89], v226 offset:5120
	s_nop 0
	s_nop 0
	v_cndmask_b32_e64 v78, v57, 0, s[18:19]
	v_cndmask_b32_e64 v79, v58, 0, s[22:23]
	v_pack_b32_f16 v77, v98, v99
	s_nop 0
	s_waitcnt lgkmcnt(1)
	v_pk_mul_f32 v[52:53], v[52:53], v[84:85]
	v_cndmask_b32_e64 v84, 0, v56, s[10:11]
	v_mfma_f32_16x16x32_f16 v[56:59], v[72:75], v[60:63], 0
	v_pack_b32_f16 v61, v78, v79
	v_mov_b32_e32 v78, v3
	v_mov_b32_e32 v79, v3
	v_mfma_f32_16x16x32_f16 v[56:59], v[68:71], v[64:67], v[56:59]
	v_mul_f32_e64 v54, v54, v86
	v_mul_f32_e64 v55, v55, v87
	v_pack_b32_f16 v60, v96, v84
	v_mov_b32_e32 v62, v3
	v_mov_b32_e32 v63, v3
	v_mfma_f32_16x16x32_f16 v[52:55], v[92:95], v[0:3], v[52:55]
	v_mfma_f32_16x16x32_f16 v[56:59], v[76:79], v[0:3], v[56:59]
	v_mad_i64_i32 v[0:1], s[26:27], v83, s91, v[122:123]
	global_store_short v[0:1], v82, off
	s_nop 0
	s_waitcnt lgkmcnt(0)
	v_mfma_f32_16x16x32_f16 v[52:55], v[88:91], v[36:39], v[52:55]
	v_subrev_u32_e32 v0, 48, v80
	v_add_u32_e32 v1, 0x7ef, v81
	v_cndmask_b32_e64 v0, v1, v0, s[2:3]
	v_mfma_f32_16x16x32_f16 v[36:39], v[60:63], v[36:39], v[56:59]
	v_add_u32_e32 v0, v0, v151
	v_mad_i64_i32 v[0:1], s[26:27], v0, s91, v[122:123]
	s_nop 5
	v_cvt_f16_f32_e32 v2, v36
	global_store_short v[0:1], v2, off
	v_subrev_u32_e32 v0, 47, v80
	v_add_u32_e32 v1, 0x7ee, v81
	v_cvt_f16_f32_e32 v2, v37
	v_cndmask_b32_e64 v0, v1, v0, s[2:3]
	v_add_u32_e32 v0, v0, v151
	v_mad_i64_i32 v[0:1], s[26:27], v0, s91, v[122:123]
	global_store_short v[0:1], v2, off
	v_subrev_u32_e32 v0, 46, v80
	v_add_u32_e32 v1, 0x7ed, v81
	v_cvt_f16_f32_e32 v2, v38
	v_cndmask_b32_e64 v0, v1, v0, s[2:3]
	v_add_u32_e32 v0, v0, v151
	v_mad_i64_i32 v[0:1], s[26:27], v0, s91, v[122:123]
	global_store_short v[0:1], v2, off
	v_subrev_u32_e32 v0, 45, v80
	v_add_u32_e32 v1, 0x7ec, v81
	v_cndmask_b32_e64 v0, v1, v0, s[2:3]
	v_cvt_f16_f32_e32 v2, v39
	v_add_u32_e32 v0, v0, v151
	v_mad_i64_i32 v[0:1], s[26:27], v0, s91, v[122:123]
	s_mov_b64 s[26:27], 0
	global_store_short v[0:1], v2, off

.LBB0_928:
	v_mov_b32_e32 v23, s47
	v_mov_b32_e32 v24, s45
	v_cndmask_b32_e64 v25, v23, v24, s[2:3]
	v_mov_b32_e32 v23, s46
	v_mov_b32_e32 v24, s44
	v_cndmask_b32_e64 v24, v23, v24, s[2:3]
	v_lshlrev_b32_e32 v23, 1, v64
	v_bfe_u32 v28, v64, 5, 1
	v_and_b32_e32 v29, 62, v23
	v_lshl_or_b32 v23, v28, 6, v29
	v_readlane_b32 s6, v255, 38
	v_lshlrev_b32_e32 v30, 2, v29
	v_readlane_b32 s7, v255, 39
	v_mad_u32_u24 v180, v23, 40, s6
	v_lshlrev_b32_e32 v23, 8, v28
	v_lshlrev_b32_e32 v31, 1, v122
	v_add3_u32 v181, s7, v23, v30
	v_lshl_add_u32 v182, v122, 2, s7
	v_add_u32_e32 v32, s6, v31
	v_readlane_b32 s6, v255, 28
	v_readlane_b32 s7, v255, 29
	v_lshl_add_u64 v[24:25], v[2:3], 1, v[24:25]
	s_lshl_b32 s6, s26, 5
	s_mov_b32 s9, s7
	v_writelane_b32 v255, s8, 28
	v_lshl_add_u64 v[24:25], v[24:25], 0, s[6:7]
	v_lshlrev_b32_e32 v26, 1, v63
	v_mov_b32_e32 v27, v3
	v_writelane_b32 v255, s9, 29
	v_lshl_add_u64 v[126:127], v[24:25], 0, v[26:27]
	v_lshlrev_b32_e32 v23, 1, v124
	v_lshlrev_b32_e32 v26, 1, v22
	v_add3_u32 v183, 0, v23, v26
	v_or3_b32 v2, v2, v21, v122
	v_lshlrev_b32_e32 v22, 2, v108
	v_mov_b32_e32 v23, v3
	v_mul_u32_u24_e32 v21, 0x900, v28
	v_lshlrev_b32_e32 v27, 1, v29
	v_readlane_b32 s27, v255, 40
	v_lshl_add_u64 v[128:129], v[40:41], 0, v[22:23]
	v_cmp_eq_u32_e32 vcc, v122, v63
	v_add3_u32 v185, s27, v21, v27
	v_lshl_or_b32 v21, v28, 4, 1
	v_or_b32_e32 v22, 1, v122
	v_lshlrev_b32_e32 v186, 6, v21
	v_mul_u32_u24_e32 v21, 0x90, v21
	v_cndmask_b32_e64 v217, 0, 1.0, vcc
	v_cmp_lt_u32_e64 s[14:15], v22, v63
	v_cmp_eq_u32_e32 vcc, v22, v63
	v_or_b32_e32 v22, 2, v122
	v_add3_u32 v187, s27, v21, v27
	v_add_u32_e32 v21, s27, v26
	v_lshlrev_b32_e32 v20, 1, v20
	v_cndmask_b32_e64 v219, 0, 1.0, vcc
	v_cmp_lt_u32_e64 s[16:17], v22, v63
	v_cmp_lt_u32_e64 s[18:19], v63, v22
	v_cmp_eq_u32_e32 vcc, v22, v63
	v_or_b32_e32 v22, 3, v122
	v_add_u32_e32 v216, v21, v20
	v_cndmask_b32_e64 v220, 0, 1.0, vcc
	v_cmp_lt_u32_e64 s[20:21], v22, v63
	v_cmp_lt_u32_e64 s[22:23], v63, v22
	v_cmp_eq_u32_e32 vcc, v22, v63
	v_add_u32_e32 v222, v21, v31
	v_or_b32_e32 v21, 16, v63
	v_mov_b32_e32 v22, s27
	v_mad_u32_u24 v21, v21, s89, v22
	v_readlane_b32 s36, v254, 53
	v_add_u32_e32 v228, v21, v20
	v_lshlrev_b32_e32 v20, 12, v28
	v_lshlrev_b64 v[0:1], 2, v[0:1]
	v_readlane_b32 s38, v254, 55
	v_readlane_b32 s39, v254, 56
	v_readlane_b32 s42, v254, 59
	v_readlane_b32 s43, v254, 60
	v_add_u32_e32 v229, v21, v31
	v_add3_u32 v234, 0, v30, v20
	v_readlane_b32 s37, v254, 54
	v_readlane_b32 s40, v254, 57
	v_readlane_b32 s41, v254, 58
	v_readlane_b32 s44, v254, 61
	v_readlane_b32 s45, v254, 62
	v_readlane_b32 s46, v254, 63
	v_readlane_b32 s47, v255, 0
	v_readlane_b32 s48, v255, 1
	v_readlane_b32 s49, v255, 2
	v_readlane_b32 s50, v255, 3
	v_readlane_b32 s51, v255, 4
	v_lshl_add_u64 v[20:21], s[38:39], 0, v[0:1]
	v_lshl_add_u64 v[0:1], s[42:43], 0, v[0:1]
	v_lshlrev_b64 v[22:23], 2, v[2:3]
	v_or_b32_e32 v24, 16, v2
	v_mov_b32_e32 v25, v3
	v_lshl_or_b32 v218, s26, 4, v63
	v_mul_u32_u24_e32 v26, 40, v63
	v_lshl_add_u64 v[130:131], v[20:21], 0, v[22:23]
	v_lshl_add_u64 v[132:133], v[0:1], 0, v[22:23]
	v_lshl_add_u64 v[134:135], s[46:47], 0, v[22:23]
	v_lshl_add_u64 v[136:137], s[48:49], 0, v[22:23]
	v_lshl_add_u64 v[138:139], s[50:51], 0, v[22:23]
	v_mov_b32_e32 v22, v3
	v_mov_b32_e32 v23, v3
	v_readlane_b32 s36, v255, 5
	v_bfe_u32 v178, v64, 6, 2
	v_lshlrev_b32_e32 v179, 10, v28
	v_mad_u32_u24 v223, v218, 40, v32
	v_mad_u32_u24 v224, v63, 40, v32
	v_add_u32_e32 v235, 0, v27
	v_mov_b32_e32 v20, v3
	v_mov_b32_e32 v21, v3
	v_add_u32_e32 v240, v32, v26
	v_lshlrev_b64 v[142:143], 1, v[24:25]
	v_mov_b64_e32 v[34:35], v[22:23]
	v_mov_b64_e32 v[30:31], v[22:23]
	v_mov_b64_e32 v[26:27], v[22:23]
	v_readlane_b32 s48, v255, 17
	s_mov_b32 s76, 0
	v_cmp_eq_u32_e64 s[4:5], 0, v178
	v_add_u32_e32 v184, 0xe000, v183
	v_cmp_gt_u32_e64 s[6:7], 8, v63
	v_cmp_eq_u32_e64 s[8:9], v66, v65
	v_mov_b32_e32 v109, v3
	v_or_b32_e32 v188, 0x80, v179
	v_add_u32_e32 v189, 0x90, v187
	v_or_b32_e32 v190, 0xc0, v179
	v_add_u32_e32 v191, 0x120, v187
	v_or_b32_e32 v192, 0x100, v179
	v_add_u32_e32 v193, 0x1b0, v187
	v_or_b32_e32 v194, 0x140, v179
	v_add_u32_e32 v195, 0x240, v187
	v_or_b32_e32 v196, 0x180, v179
	v_add_u32_e32 v197, 0x2d0, v187
	v_or_b32_e32 v198, 0x1c0, v179
	v_add_u32_e32 v199, 0x360, v187
	v_or_b32_e32 v200, 0x200, v179
	v_add_u32_e32 v201, 0x3f0, v187
	v_or_b32_e32 v202, 0x240, v179
	v_add_u32_e32 v203, 0x480, v187
	v_or_b32_e32 v204, 0x280, v179
	v_add_u32_e32 v205, 0x510, v187
	v_or_b32_e32 v206, 0x2c0, v179
	v_add_u32_e32 v207, 0x5a0, v187
	v_or_b32_e32 v208, 0x300, v179
	v_add_u32_e32 v209, 0x630, v187
	v_or_b32_e32 v210, 0x340, v179
	v_add_u32_e32 v211, 0x6c0, v187
	v_or_b32_e32 v212, 0x380, v179
	v_add_u32_e32 v213, 0x750, v187
	v_or_b32_e32 v214, 0x3c0, v179
	v_add_u32_e32 v215, 0x7e0, v187
	v_and_b32_e32 v244, 31, v238
	v_lshlrev_b32_e32 v244, 1, v244
	v_xor_b32_e32 v245, 4, v244
	v_sub_u32_e32 v245, v245, v244
	v_xor_b32_e32 v246, 8, v244
	v_sub_u32_e32 v246, v246, v244
	v_xor_b32_e32 v247, 12, v244
	v_sub_u32_e32 v247, v247, v244
	v_add_u32_e32 v188, v188, v245
	v_add_u32_e32 v190, v190, v245
	v_add_u32_e32 v192, v192, v246
	v_add_u32_e32 v194, v194, v246
	v_add_u32_e32 v196, v196, v247
	v_add_u32_e32 v198, v198, v247
	v_add_u32_e32 v204, v204, v245
	v_add_u32_e32 v206, v206, v245
	v_add_u32_e32 v208, v208, v246
	v_add_u32_e32 v210, v210, v246
	v_add_u32_e32 v212, v212, v247
	v_add_u32_e32 v214, v214, v247
	v_cmp_lt_u32_e64 s[10:11], v122, v63
	v_cmp_lt_u32_e64 s[12:13], v63, v122
	v_cndmask_b32_e64 v221, 0, 1.0, vcc
	v_add_u32_e32 v225, 0x280, v224
	v_add_u32_e32 v226, 0x500, v224
	v_add_u32_e32 v227, 0x780, v224
	v_add_u32_e32 v230, 0xa00, v224
	v_add_u32_e32 v231, 0xc80, v224
	v_add_u32_e32 v232, 0xf00, v224
	v_add_u32_e32 v233, 0x1180, v224
	v_bfe_u32 v244, v238, 4, 2
	v_xor_b32_e32 v245, 1, v244
	v_sub_u32_e32 v245, v245, v244
	v_lshlrev_b32_e32 v245, 3, v245
	v_add_u32_e32 v226, v226, v245
	v_add_u32_e32 v227, v227, v245
	v_add_u32_e32 v232, v232, v245
	v_add_u32_e32 v233, v233, v245
	v_bfe_u32 v246, v238, 7, 1
	v_xor_b32_e32 v247, v244, v246
	v_sub_u32_e32 v247, v247, v244
	v_lshlrev_b32_e32 v247, 3, v247
	v_add_u32_e32 v223, v223, v247
	v_bfe_u32 v246, v238, 4, 1
	v_bfe_u32 v247, v238, 6, 2
	v_xor_b32_e32 v246, v247, v246
	v_sub_u32_e32 v246, v246, v247
	v_lshlrev_b32_e32 v246, 3, v246
	v_add_u32_e32 v180, v180, v246
	v_sub_u32_e32 v236, 0xdf, v174
	v_sub_u32_e32 v237, 0, v62
	s_mov_b32 s77, 64
	v_lshlrev_b64 v[140:141], 1, v[2:3]
	s_mov_b32 s26, 0
	v_mov_b64_e32 v[32:33], v[20:21]
	v_mov_b64_e32 v[28:29], v[20:21]
	v_mov_b64_e32 v[24:25], v[20:21]
	v_readlane_b32 s37, v255, 6
	v_readlane_b32 s38, v255, 7
	v_readlane_b32 s39, v255, 8
	v_readlane_b32 s40, v255, 9
	v_readlane_b32 s41, v255, 10
	v_readlane_b32 s42, v255, 11
	v_readlane_b32 s43, v255, 12
	v_readlane_b32 s44, v255, 13
	v_readlane_b32 s45, v255, 14
	v_readlane_b32 s46, v255, 15
	v_readlane_b32 s47, v255, 16
	v_readlane_b32 s50, v255, 19
	v_readlane_b32 s51, v255, 20
	s_movk_i32 s48, 0x110
	s_waitcnt lgkmcnt(0)
	s_barrier
	v_readlane_b32 s49, v255, 18
	s_andn2_b64 vcc, exec, s[24:25]
	s_mov_b64 s[28:29], -1
	s_cbranch_vccnz .LBB0_936

.LBB0_935:
	s_or_b64 exec, exec, s[28:29]
	s_waitcnt lgkmcnt(0)
	s_barrier
	ds_read_b128 v[40:43], v216 offset:9216
	ds_read_b128 v[48:51], v216 offset:18496
	ds_read_b128 v[56:59], v216 offset:9280
	ds_read_b128 v[60:63], v216 offset:23040
	ds_read_b128 v[36:39], v216 offset:18432
	s_nop 0
	s_nop 0
	s_nop 0
	ds_read_b128 v[64:67], v216 offset:13824
	s_waitcnt lgkmcnt(1)
	v_mfma_f32_16x16x32_f16 v[52:55], v[40:43], v[36:39], 0
	s_nop 0
	s_nop 0
	s_nop 0
	ds_read_b128 v[68:71], v216 offset:13888
	ds_read_b128 v[72:75], v216 offset:23104
	v_add_u32_e32 v80, 0x1000, v222
	s_nop 0
	v_mfma_f32_16x16x32_f16 v[52:55], v[56:59], v[48:51], v[52:55]
	v_mov_b32_e32 v82, v3
	v_mov_b32_e32 v83, v3
	v_mov_b32_e32 v86, v3
	v_mfma_f32_16x16x32_f16 v[44:47], v[36:39], v[40:43], 0
	s_nop 3
	v_cvt_f16_f32_e32 v0, v52
	v_cvt_f16_f32_e32 v1, v54
	v_cvt_f16_f32_e32 v2, v55
	v_mfma_f32_16x16x32_f16 v[44:47], v[48:51], v[56:59], v[44:47]
	v_cndmask_b32_e64 v79, 0, v0, s[12:13]
	v_cvt_f16_f32_e32 v0, v53
	v_cndmask_b32_e64 v54, 0, v1, s[18:19]
	s_nop 0
	v_mfma_f32_16x16x32_f16 v[40:43], v[60:63], v[40:43], 0
	v_cndmask_b32_e64 v55, 0, v2, s[22:23]
	s_nop 1
	v_cndmask_b32_e64 v76, 0, v44, s[10:11]
	v_cndmask_b32_e64 v77, 0, v45, s[14:15]
	s_nop 0
	s_waitcnt lgkmcnt(2)
	v_mfma_f32_16x16x32_f16 v[36:39], v[36:39], v[64:67], 0
	v_cndmask_b32_e64 v52, 0, v46, s[16:17]
	v_cndmask_b32_e64 v78, 0, v47, s[20:21]
	v_cndmask_b32_e64 v53, v0, 0, s[10:11]
	v_mfma_f32_16x16x32_f16 v[44:47], v[60:63], v[64:67], 0
	v_cvt_pk_f16_f32 v1, v52, v78
	v_cvt_pk_f16_f32 v0, v76, v77
	v_mov_b32_e32 v2, v3
	s_nop 0
	s_waitcnt lgkmcnt(0)
	v_mfma_f32_16x16x32_f16 v[60:63], v[72:75], v[56:59], v[40:43]
	v_add_f32_e32 v56, v217, v76
	v_add_f32_e32 v57, v219, v77
	v_add_f32_e32 v58, v220, v52
	v_mfma_f32_16x16x32_f16 v[40:43], v[48:51], v[68:71], v[36:39]
	v_add_f32_e32 v59, v221, v78
	v_cvt_pk_f16_f32 v67, v26, v27
	v_cvt_pk_f16_f32 v66, v24, v25
	v_pack_b32_f16 v37, v54, v55
	v_pack_b32_f16 v36, v79, v53
	v_mov_b32_e32 v38, v3
	v_mov_b32_e32 v39, v3
	v_mfma_f32_16x16x32_f16 v[52:55], v[72:75], v[68:71], v[44:47]
	ds_read2_b64 v[68:71], v222 offset0:8 offset1:12
	v_cvt_pk_f16_f32 v65, v30, v31
	v_cvt_pk_f16_f32 v64, v28, v29
	v_mfma_f32_16x16x32_f16 v[48:51], v[0:3], v[36:39], 0
	v_cvt_pk_f16_f32 v45, v58, v59
	v_cvt_pk_f16_f32 v44, v56, v57
	v_mov_b32_e32 v46, v3
	v_mfma_f32_16x16x32_f16 v[36:39], v[36:39], v[0:3], 0
	v_mov_b32_e32 v47, v3
	s_nop 2
	v_cvt_pk_f16_f32 v1, v50, v51
	v_cvt_pk_f16_f32 v0, v48, v49
	v_mov_b32_e32 v50, v3
	v_mov_b32_e32 v51, v3
	v_cvt_pk_f16_f32 v49, v38, v39
	v_cvt_pk_f16_f32 v48, v36, v37
	v_mfma_f32_16x16x32_f16 v[44:47], v[0:3], v[44:47], v[56:59]
	v_mov_b32_e32 v87, v3
	v_mov_b32_e32 v90, v3
	v_mov_b32_e32 v91, v3
	v_mfma_f32_16x16x32_f16 v[36:39], v[48:51], v[0:3], 0
	ds_read2_b64 v[128:131], v222 offset1:4
	v_cvt_pk_f16_f32 v59, v34, v35
	v_cvt_pk_f16_f32 v58, v32, v33
	v_cvt_pk_f16_f32 v57, v22, v23
	v_mfma_f32_16x16x32_f16 v[48:51], v[0:3], v[48:51], 0
	v_cvt_pk_f16_f32 v56, v20, v21
	s_nop 2
	v_cvt_pk_f16_f32 v1, v38, v39
	v_cvt_pk_f16_f32 v0, v36, v37
	v_cvt_pk_f16_f32 v37, v46, v47
	v_cvt_pk_f16_f32 v36, v44, v45
	v_mov_b32_e32 v38, v3
	v_mov_b32_e32 v39, v3
	v_cvt_f16_f32_e32 v52, v52
	s_add_i32 s27, s26, 1
	v_mfma_f32_16x16x32_f16 v[44:47], v[0:3], v[36:39], v[44:47]
	v_cvt_pk_f16_f32 v37, v50, v51
	v_cvt_pk_f16_f32 v36, v48, v49
	v_mov_b32_e32 v50, v3
	v_mov_b32_e32 v51, v3
	v_mfma_f32_16x16x32_f16 v[36:39], v[36:39], v[0:3], 0
	s_nop 2
	v_cvt_pk_f16_f32 v1, v46, v47
	v_cvt_pk_f16_f32 v0, v44, v45
	s_nop 2
	v_cvt_pk_f16_f32 v49, v38, v39
	v_cvt_pk_f16_f32 v48, v36, v37
	s_nop 0
	s_nop 0
	s_waitcnt lgkmcnt(0)
	v_mfma_f32_16x16x32_f16 v[36:39], v[128:131], v[56:59], 0
	v_mfma_f32_16x16x32_f16 v[44:47], v[48:51], v[0:3], v[44:47]
	v_cvt_f16_f32_e32 v0, v60
	v_cvt_f16_f32_e32 v1, v61
	v_cvt_f16_f32_e32 v2, v62
	v_cvt_f16_f32_e32 v48, v63
	v_mfma_f32_16x16x32_f16 v[76:79], v[68:71], v[64:67], v[36:39]
	ds_read2_b64 v[72:75], v80 offset0:64 offset1:68
	ds_read2st64_b64 v[132:135], v223 offset0:20 offset1:25
	ds_read2_b64 v[68:71], v80 offset0:72 offset1:76
	s_nop 0
	s_nop 0
	v_cndmask_b32_e64 v0, 0, v0, s[10:11]
	v_cndmask_b32_e64 v49, 0, v1, s[14:15]
	v_cndmask_b32_e64 v1, 0, v2, s[16:17]
	v_cndmask_b32_e64 v2, 0, v48, s[20:21]
	v_pack_b32_f16 v1, v1, v2
	v_pack_b32_f16 v0, v0, v49
	v_mov_b32_e32 v2, v3
	s_nop 0
	s_waitcnt lgkmcnt(1)
	v_mov_b32_e32 v60, v132
	v_mov_b32_e32 v61, v133
	ds_read2_b64 v[128:131], v240 offset1:80
	v_mov_b32_e32 v62, v3
	v_mov_b32_e32 v63, v3
	v_cvt_f16_f32_e32 v36, v40
	ds_read_b128 v[136:139], v182
	v_cvt_f16_f32_e32 v40, v42
	v_mfma_f32_16x16x32_f16 v[48:51], v[0:3], v[60:63], v[76:79]
	v_cvt_pk_f16_f32 v1, v46, v47
	v_cvt_pk_f16_f32 v0, v44, v45
	v_cvt_f16_f32_e32 v37, v41
	v_mov_b32_e32 v78, v3
	v_mov_b32_e32 v79, v3
	s_nop 2
	v_cvt_pk_f16_f32 v77, v50, v51
	v_cvt_pk_f16_f32 v76, v48, v49
	v_cndmask_b32_e64 v88, v40, 0, s[18:19]
	v_mfma_f32_16x16x32_f16 v[56:59], v[72:75], v[56:59], 0
	v_cndmask_b32_e64 v36, v36, 0, s[12:13]
	v_cndmask_b32_e64 v37, 0, v37, s[10:11]
	v_mov_b32_e32 v74, v3
	v_mfma_f32_16x16x32_f16 v[44:47], v[0:3], v[76:79], 0
	ds_read_b64 v[76:77], v224 offset:5120
	ds_read_b128 v[140:143], v182 offset:64
	v_mov_b32_e32 v75, v3
	s_waitcnt lgkmcnt(4)
	v_mfma_f32_16x16x32_f16 v[56:59], v[68:71], v[64:67], v[56:59]
	s_nop 5
	v_cvt_pk_f16_f32 v1, v46, v47
	v_cvt_pk_f16_f32 v0, v44, v45
	s_nop 0
	s_nop 0
	s_nop 0
	s_nop 0
	s_waitcnt lgkmcnt(3)
	v_mov_b32_e32 v80, v128
	v_mov_b32_e32 v81, v129
	ds_read_b64 v[44:45], v225 offset:5120
	ds_read2_b64 v[144:147], v226 offset1:80
	s_nop 0
	s_waitcnt lgkmcnt(4)
	v_pk_mul_f32 v[50:51], v[22:23], v[138:139]
	v_pk_mul_f32 v[48:49], v[20:21], v[136:137]
	ds_read_b128 v[136:139], v182 offset:128
	s_nop 1
	v_mfma_f32_16x16x32_f16 v[48:51], v[80:83], v[0:3], v[48:51]
	v_cvt_f16_f32_e32 v80, v43
	v_cndmask_b32_e64 v89, v80, 0, s[22:23]
	s_nop 0
	s_waitcnt lgkmcnt(4)
	v_mfma_f32_16x16x32_f16 v[40:43], v[76:79], v[60:63], v[48:51]
	s_nop 3
	s_nop 0
	s_nop 0
	ds_read_b64 v[80:81], v226 offset:5120
	v_mov_b32_e32 v76, v130
	v_mov_b32_e32 v77, v131
	v_mov_b32_e32 v46, v3
	s_nop 0
	s_waitcnt lgkmcnt(4)
	v_pk_mul_f32 v[50:51], v[34:35], v[142:143]
	v_pk_mul_f32 v[48:49], v[32:33], v[140:141]
	v_mov_b32_e32 v47, v3
	ds_read_b128 v[128:131], v182 offset:192
	s_nop 0
	v_mfma_f32_16x16x32_f16 v[48:51], v[76:79], v[0:3], v[48:51]
	s_nop 0
	s_nop 0
	s_waitcnt lgkmcnt(3)
	v_mov_b32_e32 v84, v144
	v_mfma_f32_16x16x32_f16 v[48:51], v[44:47], v[60:63], v[48:51]
	s_nop 0
	s_nop 0
	v_mov_b32_e32 v85, v145
	v_pack_b32_f16 v77, v88, v89
	v_mov_b32_e32 v88, v146
	s_nop 0
	s_waitcnt lgkmcnt(2)
	v_pk_mul_f32 v[46:47], v[30:31], v[138:139]
	v_pk_mul_f32 v[44:45], v[28:29], v[136:137]
	v_mov_b32_e32 v89, v147
	v_pack_b32_f16 v76, v36, v37
	v_mfma_f32_16x16x32_f16 v[44:47], v[84:87], v[0:3], v[44:47]
	ds_read_b64 v[84:85], v227 offset:5120
	v_cndmask_b32_e64 v36, v52, 0, s[12:13]
	v_cvt_f16_f32_e32 v37, v53
	v_cndmask_b32_e64 v37, 0, v37, s[10:11]
	s_nop 0
	s_waitcnt lgkmcnt(2)
	v_mfma_f32_16x16x32_f16 v[44:47], v[80:83], v[60:63], v[44:47]
	s_nop 0
	s_nop 0
	v_pack_b32_f16 v72, v36, v37
	ds_read_b128 v[68:71], v228 offset:9216
	ds_read_b128 v[94:97], v228 offset:9280
	s_nop 0
	s_waitcnt lgkmcnt(3)
	v_pk_mul_f32 v[82:83], v[26:27], v[130:131]
	ds_read_b128 v[64:67], v228 offset:18432
	v_pk_mul_f32 v[80:81], v[24:25], v[128:129]
	s_nop 0
	ds_read_b128 v[98:101], v228 offset:23104
	v_mfma_f32_16x16x32_f16 v[78:81], v[88:91], v[0:3], v[80:83]
	ds_read_b128 v[90:93], v228 offset:18496
	s_nop 1
	v_cvt_f16_f32_e32 v82, v54
	v_cvt_f16_f32_e32 v83, v55
	s_nop 0
	s_waitcnt lgkmcnt(5)
	v_mfma_f32_16x16x32_f16 v[52:55], v[84:87], v[60:63], v[78:81]
	ds_read_b128 v[86:89], v228 offset:13824
	s_nop 1
	v_cndmask_b32_e64 v78, v82, 0, s[18:19]
	v_cndmask_b32_e64 v79, v83, 0, s[22:23]
	v_pack_b32_f16 v73, v78, v79
	v_mov_b32_e32 v78, v3
	v_mov_b32_e32 v79, v3
	v_add_u32_e32 v80, s77, v122
	v_add_u32_e32 v81, s76, v237
	v_mfma_f32_16x16x32_f16 v[56:59], v[76:79], v[0:3], v[56:59]
	ds_read_b128 v[76:79], v228 offset:23040
	v_subrev_u32_e32 v102, 64, v80
	v_add_u32_e32 v0, 0xff, v81
	v_mfma_f32_16x16x32_f16 v[58:61], v[72:75], v[60:63], v[56:59]
	v_cndmask_b32_e64 v0, v0, v102, s[2:3]
	v_add_u32_e32 v0, v0, v175
	v_mad_i64_i32 v[0:1], s[28:29], v0, s88, v[126:127]
	s_nop 0
	s_waitcnt lgkmcnt(4)
	v_mfma_f32_16x16x32_f16 v[82:85], v[68:71], v[64:67], 0
	s_nop 2
	v_cvt_f16_f32_e32 v2, v58
	v_cvt_f16_f32_e32 v60, v60
	ds_read_b128 v[128:131], v228 offset:13888
	global_store_short v[0:1], v2, off
	v_subrev_u32_e32 v0, 63, v80
	v_xad_u32 v1, v102, -2, v168
	v_cvt_f16_f32_e32 v2, v59
	s_nop 0
	v_mfma_f32_16x16x32_f16 v[72:75], v[64:67], v[68:71], 0
	v_cndmask_b32_e64 v0, v1, v0, s[2:3]
	v_add_u32_e32 v0, v0, v175
	v_mad_i64_i32 v[0:1], s[28:29], v0, s88, v[126:127]
	s_nop 0
	s_waitcnt lgkmcnt(2)
	v_mfma_f32_16x16x32_f16 v[62:65], v[64:67], v[86:89], 0
	global_store_short v[0:1], v2, off
	v_subrev_u32_e32 v0, 62, v80
	v_xad_u32 v1, v102, -3, v168
	v_mfma_f32_16x16x32_f16 v[82:85], v[94:97], v[90:93], v[82:85]
	v_cndmask_b32_e64 v36, v1, v0, s[2:3]
	v_add_u32_e32 v36, v36, v175
	s_nop 0
	s_waitcnt lgkmcnt(1)
	v_mfma_f32_16x16x32_f16 v[68:71], v[76:79], v[68:71], 0
	v_mfma_f32_16x16x32_f16 v[86:89], v[76:79], v[86:89], 0
	s_nop 2
	v_cvt_f16_f32_e32 v1, v82
	v_cvt_f16_f32_e32 v2, v83
	v_cvt_f16_f32_e32 v66, v85
	v_mfma_f32_16x16x32_f16 v[72:75], v[90:93], v[94:97], v[72:75]
	v_mov_b32_e32 v85, v3
	v_cndmask_b32_e64 v66, 0, v66, s[22:23]
	s_nop 0
	s_waitcnt lgkmcnt(0)
	v_mfma_f32_16x16x32_f16 v[76:79], v[90:93], v[128:131], v[62:65]
	v_mov_b32_e32 v92, v3
	s_nop 2
	v_cndmask_b32_e64 v0, 0, v72, s[10:11]
	v_cndmask_b32_e64 v37, 0, v73, s[14:15]
	v_cvt_f16_f32_e32 v63, v84
	v_mfma_f32_16x16x32_f16 v[94:97], v[98:101], v[94:97], v[68:71]
	v_cndmask_b32_e64 v64, 0, v74, s[16:17]
	v_cndmask_b32_e64 v65, 0, v75, s[20:21]
	v_cndmask_b32_e64 v63, 0, v63, s[18:19]
	v_cndmask_b32_e64 v68, 0, v1, s[12:13]
	v_cndmask_b32_e64 v69, v2, 0, s[10:11]
	v_add_f32_e32 v62, v217, v0
	v_cvt_pk_f16_f32 v1, v64, v65
	v_cvt_pk_f16_f32 v0, v0, v37
	v_mov_b32_e32 v2, v3
	v_pack_b32_f16 v67, v63, v66
	v_pack_b32_f16 v66, v68, v69
	v_mov_b32_e32 v68, v3
	v_mov_b32_e32 v69, v3
	v_add_f32_e32 v63, v219, v37
	v_add_f32_e32 v64, v220, v64
	v_mfma_f32_16x16x32_f16 v[70:73], v[0:3], v[66:69], 0
	v_add_f32_e32 v65, v221, v65
	v_cvt_pk_f16_f32 v83, v64, v65
	v_cvt_pk_f16_f32 v82, v62, v63
	v_mfma_f32_16x16x32_f16 v[66:69], v[66:69], v[0:3], 0
	v_mov_b32_e32 v84, v3
	s_nop 2
	v_cvt_pk_f16_f32 v0, v70, v71
	v_mov_b32_e32 v70, v3
	v_mov_b32_e32 v71, v3
	v_cvt_pk_f16_f32 v1, v72, v73
	v_cvt_pk_f16_f32 v69, v68, v69
	v_cvt_pk_f16_f32 v68, v66, v67
	v_mfma_f32_16x16x32_f16 v[62:65], v[0:3], v[82:85], v[62:65]
	v_mad_i64_i32 v[36:37], s[28:29], v36, s88, v[126:127]
	global_store_short v[36:37], v60, off
	v_mfma_f32_16x16x32_f16 v[72:75], v[68:71], v[0:3], 0
	v_cvt_f16_f32_e32 v82, v61
	v_subrev_u32_e32 v36, 61, v80
	v_xad_u32 v37, v102, -4, v168
	v_mfma_f32_16x16x32_f16 v[66:69], v[0:3], v[68:71], 0
	s_nop 0
	v_cvt_pk_f16_f32 v71, v64, v65
	s_nop 1
	v_cvt_pk_f16_f32 v1, v74, v75
	v_cvt_pk_f16_f32 v0, v72, v73
	ds_read2_b64 v[136:139], v229 offset1:4
	v_mfma_f32_16x16x32_f16 v[56:59], v[98:101], v[128:131], v[86:89]
	v_cvt_pk_f16_f32 v70, v62, v63
	v_mov_b32_e32 v72, v3
	v_mov_b32_e32 v73, v3
	v_cvt_pk_f16_f32 v85, v68, v69
	ds_read2_b64 v[128:131], v229 offset0:8 offset1:12
	v_cvt_pk_f16_f32 v84, v66, v67
	v_mov_b32_e32 v86, v3
	v_mov_b32_e32 v87, v3
	v_mfma_f32_16x16x32_f16 v[88:91], v[0:3], v[70:73], v[62:65]
	s_nop 0
	s_nop 0
	v_cndmask_b32_e64 v36, v37, v36, s[2:3]
	v_mfma_f32_16x16x32_f16 v[60:63], v[84:87], v[0:3], 0
	v_add_u32_e32 v83, v36, v175
	s_nop 2
	v_cvt_pk_f16_f32 v1, v90, v91
	v_cvt_pk_f16_f32 v0, v88, v89
	v_cvt_pk_f16_f32 v67, v54, v55
	v_cvt_pk_f16_f32 v66, v52, v53
	v_cvt_pk_f16_f32 v85, v62, v63
	v_cvt_pk_f16_f32 v84, v60, v61
	v_cvt_pk_f16_f32 v63, v50, v51
	v_cvt_pk_f16_f32 v62, v48, v49
	v_cvt_pk_f16_f32 v61, v42, v43
	v_cvt_pk_f16_f32 v60, v40, v41
	v_cvt_pk_f16_f32 v65, v46, v47
	v_cvt_pk_f16_f32 v64, v44, v45
	s_nop 0
	s_waitcnt lgkmcnt(1)
	v_mfma_f32_16x16x32_f16 v[68:71], v[136:139], v[60:63], 0
	v_add_u32_e32 v36, 0x1000, v229
	v_mov_b32_e32 v93, v3
	v_cvt_f16_f32_e32 v76, v76
	s_nop 0
	s_waitcnt lgkmcnt(0)
	v_mfma_f32_16x16x32_f16 v[98:101], v[128:131], v[64:67], v[68:71]
	ds_read2_b64 v[72:75], v36 offset0:64 offset1:68
	s_nop 1
	ds_read2_b64 v[68:71], v36 offset0:72 offset1:76
	v_cvt_f16_f32_e32 v36, v97
	v_cvt_f16_f32_e32 v97, v77
	v_mfma_f32_16x16x32_f16 v[84:87], v[84:87], v[0:3], v[88:91]
	v_cvt_f16_f32_e32 v0, v94
	v_cvt_f16_f32_e32 v1, v95
	v_cvt_f16_f32_e32 v2, v96
	v_cndmask_b32_e64 v96, v76, 0, s[12:13]
	v_cndmask_b32_e64 v0, 0, v0, s[10:11]
	v_cndmask_b32_e64 v37, 0, v1, s[14:15]
	v_cndmask_b32_e64 v1, 0, v2, s[16:17]
	v_cndmask_b32_e64 v2, 0, v36, s[20:21]
	v_pack_b32_f16 v1, v1, v2
	v_pack_b32_f16 v0, v0, v37
	v_mov_b32_e32 v2, v3
	v_mov_b32_e32 v36, v134
	v_mov_b32_e32 v37, v135
	v_mov_b32_e32 v38, v3
	v_mov_b32_e32 v39, v3
	v_mov_b32_e32 v94, v3
	v_mov_b32_e32 v95, v3
	v_mfma_f32_16x16x32_f16 v[88:91], v[0:3], v[36:39], v[98:101]
	v_cvt_pk_f16_f32 v1, v86, v87
	v_cvt_pk_f16_f32 v0, v84, v85
	v_cvt_f16_f32_e32 v56, v56
	v_cvt_f16_f32_e32 v98, v78
	v_cvt_f16_f32_e32 v99, v79
	s_nop 2
	v_cvt_pk_f16_f32 v91, v90, v91
	v_cvt_pk_f16_f32 v90, v88, v89
	v_cndmask_b32_e64 v97, 0, v97, s[10:11]
	v_cndmask_b32_e64 v98, v98, 0, s[18:19]
	v_mfma_f32_16x16x32_f16 v[84:87], v[0:3], v[90:93], 0
	v_add_u32_e32 v2, 0x800, v240
	ds_read2_b64 v[128:131], v2 offset0:64 offset1:144
	ds_read_b128 v[76:79], v182 offset:256
	v_mov_b32_e32 v90, v3
	v_mov_b32_e32 v91, v3
	v_cndmask_b32_e64 v99, v99, 0, s[22:23]
	ds_read_b64 v[88:89], v230 offset:5120
	ds_read_b128 v[132:135], v182 offset:320
	s_nop 3
	v_cvt_pk_f16_f32 v1, v86, v87
	v_cvt_pk_f16_f32 v0, v84, v85
	s_nop 0
	s_nop 0
	s_nop 0
	v_mov_b32_e32 v2, v3
	s_nop 0
	s_waitcnt lgkmcnt(3)
	v_mov_b32_e32 v92, v128
	v_mov_b32_e32 v93, v129
	ds_read_b64 v[84:85], v231 offset:5120
	s_nop 0
	s_waitcnt lgkmcnt(3)
	v_pk_mul_f32 v[42:43], v[42:43], v[78:79]
	v_pk_mul_f32 v[40:41], v[40:41], v[76:77]
	s_nop 0
	s_nop 0
	v_mfma_f32_16x16x32_f16 v[40:43], v[92:95], v[0:3], v[40:43]
	s_nop 0
	s_waitcnt lgkmcnt(1)
	v_pk_mul_f32 v[48:49], v[48:49], v[132:133]
	v_add_u32_e32 v76, 0xc00, v240
	ds_read2_b64 v[136:139], v232 offset1:80
	ds_read_b128 v[140:143], v182 offset:384
	v_mfma_f32_16x16x32_f16 v[40:43], v[88:91], v[36:39], v[40:43]
	v_mov_b32_e32 v88, v130
	v_mov_b32_e32 v89, v131
	v_pk_mul_f32 v[50:51], v[50:51], v[134:135]
	v_mov_b32_e32 v86, v3
	v_mov_b32_e32 v87, v3
	s_nop 0
	v_mfma_f32_16x16x32_f16 v[48:51], v[88:91], v[0:3], v[48:51]
	ds_read_b64 v[88:89], v232 offset:5120
	s_nop 0
	s_waitcnt lgkmcnt(2)
	v_mov_b32_e32 v92, v136
	v_mfma_f32_16x16x32_f16 v[48:51], v[84:87], v[36:39], v[48:51]
	s_nop 0
	s_nop 0
	v_mov_b32_e32 v93, v137
	v_pack_b32_f16 v76, v96, v97
	v_cndmask_b32_e64 v96, v56, 0, s[12:13]
	s_nop 0
	s_waitcnt lgkmcnt(1)
	v_pk_mul_f32 v[46:47], v[46:47], v[142:143]
	v_pk_mul_f32 v[44:45], v[44:45], v[140:141]
	ds_read_b128 v[84:87], v182 offset:448
	v_cvt_f16_f32_e32 v56, v57
	v_cvt_f16_f32_e32 v57, v58
	v_mfma_f32_16x16x32_f16 v[44:47], v[92:95], v[0:3], v[44:47]
	v_cvt_f16_f32_e32 v58, v59
	v_mov_b32_e32 v92, v138
	v_mov_b32_e32 v93, v139
	s_nop 0
	s_waitcnt lgkmcnt(1)
	v_mfma_f32_16x16x32_f16 v[44:47], v[88:91], v[36:39], v[44:47]
	ds_read_b64 v[88:89], v233 offset:5120
	s_nop 0
	s_nop 0
	v_cndmask_b32_e64 v78, v57, 0, s[18:19]
	v_cndmask_b32_e64 v79, v58, 0, s[22:23]
	v_pack_b32_f16 v77, v98, v99
	s_nop 0
	s_waitcnt lgkmcnt(1)
	v_pk_mul_f32 v[52:53], v[52:53], v[84:85]
	v_cndmask_b32_e64 v84, 0, v56, s[10:11]
	v_mfma_f32_16x16x32_f16 v[56:59], v[72:75], v[60:63], 0
	v_pack_b32_f16 v61, v78, v79
	v_mov_b32_e32 v78, v3
	v_mov_b32_e32 v79, v3
	v_mfma_f32_16x16x32_f16 v[56:59], v[68:71], v[64:67], v[56:59]
	v_mul_f32_e64 v54, v54, v86
	v_mul_f32_e64 v55, v55, v87
	v_pack_b32_f16 v60, v96, v84
	v_mov_b32_e32 v62, v3
	v_mov_b32_e32 v63, v3
	v_mfma_f32_16x16x32_f16 v[52:55], v[92:95], v[0:3], v[52:55]
	v_mfma_f32_16x16x32_f16 v[56:59], v[76:79], v[0:3], v[56:59]
	v_mad_i64_i32 v[0:1], s[28:29], v83, s88, v[126:127]
	global_store_short v[0:1], v82, off
	s_nop 0
	s_waitcnt lgkmcnt(0)
	v_mfma_f32_16x16x32_f16 v[52:55], v[88:91], v[36:39], v[52:55]
	v_subrev_u32_e32 v0, 48, v80
	v_add_u32_e32 v1, 0xef, v81
	v_cndmask_b32_e64 v0, v1, v0, s[2:3]
	v_mfma_f32_16x16x32_f16 v[36:39], v[60:63], v[36:39], v[56:59]
	v_add_u32_e32 v0, v0, v175
	v_mad_i64_i32 v[0:1], s[28:29], v0, s88, v[126:127]
	s_nop 5
	v_cvt_f16_f32_e32 v2, v36
	global_store_short v[0:1], v2, off
	v_subrev_u32_e32 v0, 47, v80
	v_add_u32_e32 v1, 0xee, v81
	v_cvt_f16_f32_e32 v2, v37
	v_cndmask_b32_e64 v0, v1, v0, s[2:3]
	v_add_u32_e32 v0, v0, v175
	v_mad_i64_i32 v[0:1], s[28:29], v0, s88, v[126:127]
	global_store_short v[0:1], v2, off
	v_subrev_u32_e32 v0, 46, v80
	v_add_u32_e32 v1, 0xed, v81
	v_cvt_f16_f32_e32 v2, v38
	v_cndmask_b32_e64 v0, v1, v0, s[2:3]
	v_add_u32_e32 v0, v0, v175
	v_mad_i64_i32 v[0:1], s[28:29], v0, s88, v[126:127]
	global_store_short v[0:1], v2, off
	v_subrev_u32_e32 v0, 45, v80
	v_add_u32_e32 v1, 0xec, v81
	v_cndmask_b32_e64 v0, v1, v0, s[2:3]
	v_cvt_f16_f32_e32 v2, v39
	v_add_u32_e32 v0, v0, v175
	v_mad_i64_i32 v[0:1], s[28:29], v0, s88, v[126:127]
	s_mov_b64 s[28:29], 0
	global_store_short v[0:1], v2, off

.LBB0_1025:
	v_mov_b32_e32 v1, s47
	s_waitcnt lgkmcnt(6)
	v_mov_b32_e32 v2, s45
	v_cndmask_b32_e64 v43, v1, v2, s[2:3]
	v_mov_b32_e32 v1, s46
	v_mov_b32_e32 v2, s44
	v_cndmask_b32_e64 v42, v1, v2, s[2:3]
	v_lshlrev_b32_e32 v1, 1, v76
	v_bfe_u32 v44, v76, 5, 1
	v_and_b32_e32 v45, 62, v1
	v_lshl_or_b32 v1, v44, 6, v45
	v_readlane_b32 s6, v255, 38
	v_lshlrev_b32_e32 v46, 2, v45
	v_readlane_b32 s7, v255, 39
	v_mad_u32_u24 v176, v1, 40, s6
	v_lshlrev_b32_e32 v1, 8, v44
	s_waitcnt vmcnt(0)
	v_lshlrev_b32_e32 v47, 1, v153
	v_add3_u32 v177, s7, v1, v46
	v_lshl_add_u32 v178, v153, 2, s7
	v_add_u32_e32 v48, s6, v47
	v_ashrrev_i32_e32 v37, 31, v36
	v_readlane_b32 s6, v255, 28
	v_lshl_add_u64 v[42:43], v[36:37], 1, v[42:43]
	v_readlane_b32 s7, v255, 29
	s_lshl_b32 s6, s8, 1
	s_mov_b32 s9, s7
	v_lshl_add_u64 v[42:43], v[42:43], 0, s[6:7]
	v_lshlrev_b32_e32 v2, 1, v74
	v_writelane_b32 v255, s8, 28
	v_lshl_add_u64 v[122:123], v[42:43], 0, v[2:3]
	v_lshlrev_b32_e32 v1, 1, v120
	v_lshlrev_b32_e32 v2, 1, v40
	v_writelane_b32 v255, s9, 29
	v_add3_u32 v179, 0, v1, v2
	v_ashrrev_i32_e32 v1, 31, v0
	v_lshl_add_u64 v[124:125], v[0:1], 2, v[58:59]
	v_mul_u32_u24_e32 v0, 0x900, v44
	v_lshlrev_b32_e32 v45, 1, v45
	v_readlane_b32 s26, v255, 40
	v_lshlrev_b32_e32 v1, 1, v38
	v_or3_b32 v36, v36, v39, v153
	v_add3_u32 v181, s26, v0, v45
	v_lshl_or_b32 v0, v44, 4, 1
	v_lshlrev_b32_e32 v182, 6, v0
	v_mul_u32_u24_e32 v0, 0x90, v0
	v_add3_u32 v183, s26, v0, v45
	v_add_u32_e32 v0, s26, v2
	v_add_u32_e32 v212, v0, v1
	v_add_u32_e32 v217, v0, v47
	v_or_b32_e32 v0, 16, v74
	v_mov_b32_e32 v38, s26
	v_cmp_eq_u32_e32 vcc, v153, v74
	v_or_b32_e32 v2, 1, v153
	v_mad_u32_u24 v0, v0, s89, v38
	v_ashrrev_i32_e32 v37, 31, v36
	v_cndmask_b32_e64 v213, 0, 1.0, vcc
	v_cmp_lt_u32_e64 s[14:15], v2, v74
	v_cmp_eq_u32_e32 vcc, v2, v74
	v_or_b32_e32 v2, 2, v153
	v_add_u32_e32 v223, v0, v1
	v_add_u32_e32 v224, v0, v47
	v_lshlrev_b32_e32 v0, 12, v44
	v_readlane_b32 s36, v254, 53
	v_or_b32_e32 v40, 16, v36
	v_cndmask_b32_e64 v214, 0, 1.0, vcc
	v_cmp_lt_u32_e64 s[16:17], v2, v74
	v_cmp_lt_u32_e64 s[18:19], v74, v2
	v_cmp_eq_u32_e32 vcc, v2, v74
	v_or_b32_e32 v2, 3, v153
	v_add3_u32 v229, 0, v46, v0
	v_lshlrev_b64 v[0:1], 2, v[56:57]
	v_readlane_b32 s37, v254, 54
	v_readlane_b32 s38, v254, 55
	v_readlane_b32 s39, v254, 56
	v_readlane_b32 s40, v254, 57
	v_readlane_b32 s41, v254, 58
	v_readlane_b32 s42, v254, 59
	v_readlane_b32 s43, v254, 60
	v_readlane_b32 s44, v254, 61
	v_readlane_b32 s45, v254, 62
	v_readlane_b32 s46, v254, 63
	v_readlane_b32 s47, v255, 0
	v_lshlrev_b64 v[42:43], 2, v[36:37]
	v_bfe_u32 v174, v76, 6, 2
	v_lshlrev_b32_e32 v175, 10, v44
	v_ashrrev_i32_e32 v41, 31, v40
	v_cndmask_b32_e64 v215, 0, 1.0, vcc
	v_cmp_lt_u32_e64 s[20:21], v2, v74
	v_cmp_lt_u32_e64 s[22:23], v74, v2
	v_cmp_eq_u32_e32 vcc, v2, v74
	v_mul_u32_u24_e32 v2, 40, v74
	v_mad_u32_u24 v219, v74, 40, v48
	v_readlane_b32 s48, v255, 1
	v_readlane_b32 s49, v255, 2
	v_readlane_b32 s50, v255, 3
	v_readlane_b32 s51, v255, 4
	v_lshl_add_u64 v[38:39], s[38:39], 0, v[0:1]
	v_lshl_add_u64 v[0:1], s[42:43], 0, v[0:1]
	v_lshl_add_u64 v[130:131], s[46:47], 0, v[42:43]
	s_mov_b64 s[36:37], s[52:53]
	s_mov_b32 s68, 0
	v_cmp_eq_u32_e64 s[4:5], 0, v174
	v_add_u32_e32 v180, 0xe000, v179
	v_cmp_gt_u32_e64 s[6:7], 8, v74
	v_cmp_eq_u32_e64 s[8:9], v78, v79
	v_or_b32_e32 v184, 0x80, v175
	v_add_u32_e32 v185, 0x90, v183
	v_or_b32_e32 v186, 0xc0, v175
	v_add_u32_e32 v187, 0x120, v183
	v_or_b32_e32 v188, 0x100, v175
	v_add_u32_e32 v189, 0x1b0, v183
	v_or_b32_e32 v190, 0x140, v175
	v_add_u32_e32 v191, 0x240, v183
	v_or_b32_e32 v192, 0x180, v175
	v_add_u32_e32 v193, 0x2d0, v183
	v_or_b32_e32 v194, 0x1c0, v175
	v_add_u32_e32 v195, 0x360, v183
	v_or_b32_e32 v196, 0x200, v175
	v_add_u32_e32 v197, 0x3f0, v183
	v_or_b32_e32 v198, 0x240, v175
	v_add_u32_e32 v199, 0x480, v183
	v_or_b32_e32 v200, 0x280, v175
	v_add_u32_e32 v201, 0x510, v183
	v_or_b32_e32 v202, 0x2c0, v175
	v_add_u32_e32 v203, 0x5a0, v183
	v_or_b32_e32 v204, 0x300, v175
	v_add_u32_e32 v205, 0x630, v183
	v_or_b32_e32 v206, 0x340, v175
	v_add_u32_e32 v207, 0x6c0, v183
	v_or_b32_e32 v208, 0x380, v175
	v_add_u32_e32 v209, 0x750, v183
	v_or_b32_e32 v210, 0x3c0, v175
	v_add_u32_e32 v211, 0x7e0, v183
	v_and_b32_e32 v244, 31, v238
	v_lshlrev_b32_e32 v244, 1, v244
	v_xor_b32_e32 v245, 4, v244
	v_sub_u32_e32 v245, v245, v244
	v_xor_b32_e32 v246, 8, v244
	v_sub_u32_e32 v246, v246, v244
	v_xor_b32_e32 v247, 12, v244
	v_sub_u32_e32 v247, v247, v244
	v_add_u32_e32 v184, v184, v245
	v_add_u32_e32 v186, v186, v245
	v_add_u32_e32 v188, v188, v246
	v_add_u32_e32 v190, v190, v246
	v_add_u32_e32 v192, v192, v247
	v_add_u32_e32 v194, v194, v247
	v_add_u32_e32 v200, v200, v245
	v_add_u32_e32 v202, v202, v245
	v_add_u32_e32 v204, v204, v246
	v_add_u32_e32 v206, v206, v246
	v_add_u32_e32 v208, v208, v247
	v_add_u32_e32 v210, v210, v247
	v_cmp_lt_u32_e64 s[10:11], v153, v74
	v_cmp_lt_u32_e64 s[12:13], v74, v153
	v_cndmask_b32_e64 v216, 0, 1.0, vcc
	v_mad_u32_u24 v218, v75, 40, v48
	v_add_u32_e32 v220, 0x280, v219
	v_add_u32_e32 v221, 0x500, v219
	v_add_u32_e32 v222, 0x780, v219
	v_add_u32_e32 v225, 0xa00, v219
	v_add_u32_e32 v226, 0xc80, v219
	v_add_u32_e32 v227, 0xf00, v219
	v_add_u32_e32 v228, 0x1180, v219
	v_bfe_u32 v244, v238, 4, 2
	v_xor_b32_e32 v245, 1, v244
	v_sub_u32_e32 v245, v245, v244
	v_lshlrev_b32_e32 v245, 3, v245
	v_add_u32_e32 v221, v221, v245
	v_add_u32_e32 v222, v222, v245
	v_add_u32_e32 v227, v227, v245
	v_add_u32_e32 v228, v228, v245
	v_bfe_u32 v246, v238, 7, 1
	v_xor_b32_e32 v247, v244, v246
	v_sub_u32_e32 v247, v247, v244
	v_lshlrev_b32_e32 v247, 3, v247
	v_add_u32_e32 v218, v218, v247
	v_bfe_u32 v246, v238, 4, 1
	v_bfe_u32 v247, v238, 6, 2
	v_xor_b32_e32 v246, v247, v246
	v_sub_u32_e32 v246, v246, v247
	v_lshlrev_b32_e32 v246, 3, v246
	v_add_u32_e32 v176, v176, v246
	v_lshl_add_u64 v[126:127], v[38:39], 0, v[42:43]
	v_lshl_add_u64 v[128:129], v[0:1], 0, v[42:43]
	v_lshl_add_u64 v[132:133], s[48:49], 0, v[42:43]
	v_lshl_add_u64 v[134:135], s[50:51], 0, v[42:43]
	v_add_u32_e32 v230, 0, v45
	v_sub_u32_e32 v231, 0x7df, v150
	v_sub_u32_e32 v232, 0, v77
	s_mov_b32 s69, 64
	v_add_u32_e32 v233, v48, v2
	v_lshlrev_b64 v[136:137], 1, v[36:37]
	v_lshlrev_b64 v[138:139], 1, v[40:41]
	s_mov_b32 s76, 0
	s_mov_b64 s[38:39], s[54:55]
	s_mov_b64 s[40:41], s[56:57]
	s_mov_b64 s[42:43], s[58:59]
	s_mov_b64 s[44:45], s[60:61]
	s_mov_b64 s[46:47], s[62:63]
	s_mov_b64 s[50:51], s[66:67]
	s_movk_i32 s48, 0x110
	s_waitcnt lgkmcnt(0)
	s_barrier
	s_branch .LBB0_1028

.LBB0_1035:
	s_or_b64 exec, exec, s[26:27]
	s_waitcnt lgkmcnt(0)
	s_barrier
	ds_read_b128 v[40:43], v212 offset:9216
	ds_read_b128 v[48:51], v212 offset:18496
	ds_read_b128 v[56:59], v212 offset:9280
	ds_read_b128 v[60:63], v212 offset:23040
	ds_read_b128 v[36:39], v212 offset:18432
	s_nop 0
	s_nop 0
	s_nop 0
	ds_read_b128 v[64:67], v212 offset:13824
	s_waitcnt lgkmcnt(1)
	v_mfma_f32_16x16x32_f16 v[52:55], v[40:43], v[36:39], 0
	s_nop 0
	s_nop 0
	s_nop 0
	ds_read_b128 v[68:71], v212 offset:13888
	ds_read_b128 v[72:75], v212 offset:23104
	v_add_u32_e32 v80, 0x1000, v217
	s_nop 0
	v_mfma_f32_16x16x32_f16 v[52:55], v[56:59], v[48:51], v[52:55]
	v_mov_b32_e32 v82, v3
	v_mov_b32_e32 v83, v3
	v_mov_b32_e32 v86, v3
	v_mfma_f32_16x16x32_f16 v[44:47], v[36:39], v[40:43], 0
	s_nop 3
	v_cvt_f16_f32_e32 v0, v52
	v_cvt_f16_f32_e32 v1, v54
	v_cvt_f16_f32_e32 v2, v55
	v_mfma_f32_16x16x32_f16 v[44:47], v[48:51], v[56:59], v[44:47]
	v_cndmask_b32_e64 v79, 0, v0, s[12:13]
	v_cvt_f16_f32_e32 v0, v53
	v_cndmask_b32_e64 v54, 0, v1, s[18:19]
	s_nop 0
	v_mfma_f32_16x16x32_f16 v[40:43], v[60:63], v[40:43], 0
	v_cndmask_b32_e64 v55, 0, v2, s[22:23]
	s_nop 1
	v_cndmask_b32_e64 v76, 0, v44, s[10:11]
	v_cndmask_b32_e64 v77, 0, v45, s[14:15]
	s_nop 0
	s_waitcnt lgkmcnt(2)
	v_mfma_f32_16x16x32_f16 v[36:39], v[36:39], v[64:67], 0
	v_cndmask_b32_e64 v52, 0, v46, s[16:17]
	v_cndmask_b32_e64 v78, 0, v47, s[20:21]
	v_cndmask_b32_e64 v53, v0, 0, s[10:11]
	v_mfma_f32_16x16x32_f16 v[44:47], v[60:63], v[64:67], 0
	v_cvt_pk_f16_f32 v1, v52, v78
	v_cvt_pk_f16_f32 v0, v76, v77
	v_mov_b32_e32 v2, v3
	s_nop 0
	s_waitcnt lgkmcnt(0)
	v_mfma_f32_16x16x32_f16 v[60:63], v[72:75], v[56:59], v[40:43]
	v_add_f32_e32 v56, v213, v76
	v_add_f32_e32 v57, v214, v77
	v_add_f32_e32 v58, v215, v52
	v_mfma_f32_16x16x32_f16 v[40:43], v[48:51], v[68:71], v[36:39]
	v_add_f32_e32 v59, v216, v78
	v_cvt_pk_f16_f32 v67, v18, v19
	v_cvt_pk_f16_f32 v66, v16, v17
	v_pack_b32_f16 v37, v54, v55
	v_pack_b32_f16 v36, v79, v53
	v_mov_b32_e32 v38, v3
	v_mov_b32_e32 v39, v3
	v_mfma_f32_16x16x32_f16 v[52:55], v[72:75], v[68:71], v[44:47]
	ds_read2_b64 v[68:71], v217 offset0:8 offset1:12
	v_cvt_pk_f16_f32 v65, v14, v15
	v_cvt_pk_f16_f32 v64, v12, v13
	v_mfma_f32_16x16x32_f16 v[48:51], v[0:3], v[36:39], 0
	v_cvt_pk_f16_f32 v45, v58, v59
	v_cvt_pk_f16_f32 v44, v56, v57
	v_mov_b32_e32 v46, v3
	v_mfma_f32_16x16x32_f16 v[36:39], v[36:39], v[0:3], 0
	v_mov_b32_e32 v47, v3
	s_nop 2
	v_cvt_pk_f16_f32 v1, v50, v51
	v_cvt_pk_f16_f32 v0, v48, v49
	v_mov_b32_e32 v50, v3
	v_mov_b32_e32 v51, v3
	v_cvt_pk_f16_f32 v49, v38, v39
	v_cvt_pk_f16_f32 v48, v36, v37
	v_mfma_f32_16x16x32_f16 v[44:47], v[0:3], v[44:47], v[56:59]
	v_mov_b32_e32 v87, v3
	v_mov_b32_e32 v90, v3
	v_mov_b32_e32 v91, v3
	v_mfma_f32_16x16x32_f16 v[36:39], v[48:51], v[0:3], 0
	ds_read2_b64 v[126:129], v217 offset1:4
	v_cvt_pk_f16_f32 v59, v10, v11
	v_cvt_pk_f16_f32 v58, v8, v9
	v_cvt_pk_f16_f32 v57, v6, v7
	v_mfma_f32_16x16x32_f16 v[48:51], v[0:3], v[48:51], 0
	v_cvt_pk_f16_f32 v56, v4, v5
	s_nop 2
	v_cvt_pk_f16_f32 v1, v38, v39
	v_cvt_pk_f16_f32 v0, v36, v37
	v_cvt_pk_f16_f32 v37, v46, v47
	v_cvt_pk_f16_f32 v36, v44, v45
	v_mov_b32_e32 v38, v3
	v_mov_b32_e32 v39, v3
	v_cvt_f16_f32_e32 v52, v52
	s_add_i32 s28, s76, 1
	v_mfma_f32_16x16x32_f16 v[44:47], v[0:3], v[36:39], v[44:47]
	v_cvt_pk_f16_f32 v37, v50, v51
	v_cvt_pk_f16_f32 v36, v48, v49
	v_mov_b32_e32 v50, v3
	v_mov_b32_e32 v51, v3
	v_mfma_f32_16x16x32_f16 v[36:39], v[36:39], v[0:3], 0
	s_nop 2
	v_cvt_pk_f16_f32 v1, v46, v47
	v_cvt_pk_f16_f32 v0, v44, v45
	s_nop 2
	v_cvt_pk_f16_f32 v49, v38, v39
	v_cvt_pk_f16_f32 v48, v36, v37
	s_nop 0
	s_nop 0
	s_waitcnt lgkmcnt(0)
	v_mfma_f32_16x16x32_f16 v[36:39], v[126:129], v[56:59], 0
	v_mfma_f32_16x16x32_f16 v[44:47], v[48:51], v[0:3], v[44:47]
	v_cvt_f16_f32_e32 v0, v60
	v_cvt_f16_f32_e32 v1, v61
	v_cvt_f16_f32_e32 v2, v62
	v_cvt_f16_f32_e32 v48, v63
	v_mfma_f32_16x16x32_f16 v[76:79], v[68:71], v[64:67], v[36:39]
	ds_read2_b64 v[72:75], v80 offset0:64 offset1:68
	ds_read2st64_b64 v[130:133], v218 offset0:20 offset1:25
	ds_read2_b64 v[68:71], v80 offset0:72 offset1:76
	s_nop 0
	s_nop 0
	v_cndmask_b32_e64 v0, 0, v0, s[10:11]
	v_cndmask_b32_e64 v49, 0, v1, s[14:15]
	v_cndmask_b32_e64 v1, 0, v2, s[16:17]
	v_cndmask_b32_e64 v2, 0, v48, s[20:21]
	v_pack_b32_f16 v1, v1, v2
	v_pack_b32_f16 v0, v0, v49
	v_mov_b32_e32 v2, v3
	s_nop 0
	s_waitcnt lgkmcnt(1)
	v_mov_b32_e32 v60, v130
	v_mov_b32_e32 v61, v131
	ds_read2_b64 v[126:129], v233 offset1:80
	v_mov_b32_e32 v62, v3
	v_mov_b32_e32 v63, v3
	v_cvt_f16_f32_e32 v36, v40
	ds_read_b128 v[134:137], v178
	v_cvt_f16_f32_e32 v40, v42
	v_mfma_f32_16x16x32_f16 v[48:51], v[0:3], v[60:63], v[76:79]
	v_cvt_pk_f16_f32 v1, v46, v47
	v_cvt_pk_f16_f32 v0, v44, v45
	v_cvt_f16_f32_e32 v37, v41
	v_mov_b32_e32 v78, v3
	v_mov_b32_e32 v79, v3
	s_nop 2
	v_cvt_pk_f16_f32 v77, v50, v51
	v_cvt_pk_f16_f32 v76, v48, v49
	v_cndmask_b32_e64 v88, v40, 0, s[18:19]
	v_mfma_f32_16x16x32_f16 v[56:59], v[72:75], v[56:59], 0
	v_cndmask_b32_e64 v36, v36, 0, s[12:13]
	v_cndmask_b32_e64 v37, 0, v37, s[10:11]
	v_mov_b32_e32 v74, v3
	v_mfma_f32_16x16x32_f16 v[44:47], v[0:3], v[76:79], 0
	ds_read_b64 v[76:77], v219 offset:5120
	ds_read_b128 v[138:141], v178 offset:64
	v_mov_b32_e32 v75, v3
	s_waitcnt lgkmcnt(4)
	v_mfma_f32_16x16x32_f16 v[56:59], v[68:71], v[64:67], v[56:59]
	s_nop 5
	v_cvt_pk_f16_f32 v1, v46, v47
	v_cvt_pk_f16_f32 v0, v44, v45
	s_nop 0
	s_nop 0
	s_nop 0
	s_nop 0
	s_waitcnt lgkmcnt(3)
	v_mov_b32_e32 v80, v126
	v_mov_b32_e32 v81, v127
	ds_read_b64 v[44:45], v220 offset:5120
	ds_read2_b64 v[142:145], v221 offset1:80
	s_nop 0
	s_waitcnt lgkmcnt(4)
	v_pk_mul_f32 v[50:51], v[6:7], v[136:137]
	v_pk_mul_f32 v[48:49], v[4:5], v[134:135]
	ds_read_b128 v[134:137], v178 offset:128
	s_nop 1
	v_mfma_f32_16x16x32_f16 v[48:51], v[80:83], v[0:3], v[48:51]
	v_cvt_f16_f32_e32 v80, v43
	v_cndmask_b32_e64 v89, v80, 0, s[22:23]
	s_nop 0
	s_waitcnt lgkmcnt(4)
	v_mfma_f32_16x16x32_f16 v[40:43], v[76:79], v[60:63], v[48:51]
	s_nop 3
	s_nop 0
	s_nop 0
	ds_read_b64 v[80:81], v221 offset:5120
	v_mov_b32_e32 v76, v128
	v_mov_b32_e32 v77, v129
	v_mov_b32_e32 v46, v3
	s_nop 0
	s_waitcnt lgkmcnt(4)
	v_pk_mul_f32 v[50:51], v[10:11], v[140:141]
	v_pk_mul_f32 v[48:49], v[8:9], v[138:139]
	v_mov_b32_e32 v47, v3
	ds_read_b128 v[126:129], v178 offset:192
	s_nop 0
	v_mfma_f32_16x16x32_f16 v[48:51], v[76:79], v[0:3], v[48:51]
	s_nop 0
	s_nop 0
	s_waitcnt lgkmcnt(3)
	v_mov_b32_e32 v84, v142
	v_mfma_f32_16x16x32_f16 v[48:51], v[44:47], v[60:63], v[48:51]
	s_nop 0
	s_nop 0
	v_mov_b32_e32 v85, v143
	v_pack_b32_f16 v77, v88, v89
	v_mov_b32_e32 v88, v144
	s_nop 0
	s_waitcnt lgkmcnt(2)
	v_pk_mul_f32 v[46:47], v[14:15], v[136:137]
	v_pk_mul_f32 v[44:45], v[12:13], v[134:135]
	v_mov_b32_e32 v89, v145
	v_pack_b32_f16 v76, v36, v37
	v_mfma_f32_16x16x32_f16 v[44:47], v[84:87], v[0:3], v[44:47]
	ds_read_b64 v[84:85], v222 offset:5120
	v_cndmask_b32_e64 v36, v52, 0, s[12:13]
	v_cvt_f16_f32_e32 v37, v53
	v_cndmask_b32_e64 v37, 0, v37, s[10:11]
	s_nop 0
	s_waitcnt lgkmcnt(2)
	v_mfma_f32_16x16x32_f16 v[44:47], v[80:83], v[60:63], v[44:47]
	s_nop 0
	s_nop 0
	v_pack_b32_f16 v72, v36, v37
	ds_read_b128 v[68:71], v223 offset:9216
	ds_read_b128 v[94:97], v223 offset:9280
	s_nop 0
	s_waitcnt lgkmcnt(3)
	v_pk_mul_f32 v[82:83], v[18:19], v[128:129]
	ds_read_b128 v[64:67], v223 offset:18432
	v_pk_mul_f32 v[80:81], v[16:17], v[126:127]
	s_nop 0
	ds_read_b128 v[98:101], v223 offset:23104
	v_mfma_f32_16x16x32_f16 v[78:81], v[88:91], v[0:3], v[80:83]
	ds_read_b128 v[90:93], v223 offset:18496
	s_nop 1
	v_cvt_f16_f32_e32 v82, v54
	v_cvt_f16_f32_e32 v83, v55
	s_nop 0
	s_waitcnt lgkmcnt(5)
	v_mfma_f32_16x16x32_f16 v[52:55], v[84:87], v[60:63], v[78:81]
	ds_read_b128 v[86:89], v223 offset:13824
	s_nop 1
	v_cndmask_b32_e64 v78, v82, 0, s[18:19]
	v_cndmask_b32_e64 v79, v83, 0, s[22:23]
	v_pack_b32_f16 v73, v78, v79
	v_mov_b32_e32 v78, v3
	v_mov_b32_e32 v79, v3
	v_add_u32_e32 v80, s69, v153
	v_add_u32_e32 v81, s68, v232
	v_mfma_f32_16x16x32_f16 v[56:59], v[76:79], v[0:3], v[56:59]
	ds_read_b128 v[76:79], v223 offset:23040
	v_subrev_u32_e32 v102, 64, v80
	v_add_u32_e32 v0, 0x7ff, v81
	v_mfma_f32_16x16x32_f16 v[58:61], v[72:75], v[60:63], v[56:59]
	v_cndmask_b32_e64 v0, v0, v102, s[2:3]
	v_add_u32_e32 v0, v0, v151
	v_mad_i64_i32 v[0:1], s[26:27], v0, s88, v[122:123]
	s_nop 0
	s_waitcnt lgkmcnt(4)
	v_mfma_f32_16x16x32_f16 v[82:85], v[68:71], v[64:67], 0
	s_nop 2
	v_cvt_f16_f32_e32 v2, v58
	v_cvt_f16_f32_e32 v60, v60
	ds_read_b128 v[126:129], v223 offset:13888
	global_store_short v[0:1], v2, off
	v_subrev_u32_e32 v0, 63, v80
	v_xad_u32 v1, v102, -2, v172
	v_cvt_f16_f32_e32 v2, v59
	s_nop 0
	v_mfma_f32_16x16x32_f16 v[72:75], v[64:67], v[68:71], 0
	v_cndmask_b32_e64 v0, v1, v0, s[2:3]
	v_add_u32_e32 v0, v0, v151
	v_mad_i64_i32 v[0:1], s[26:27], v0, s88, v[122:123]
	s_nop 0
	s_waitcnt lgkmcnt(2)
	v_mfma_f32_16x16x32_f16 v[62:65], v[64:67], v[86:89], 0
	global_store_short v[0:1], v2, off
	v_subrev_u32_e32 v0, 62, v80
	v_xad_u32 v1, v102, -3, v172
	v_mfma_f32_16x16x32_f16 v[82:85], v[94:97], v[90:93], v[82:85]
	v_cndmask_b32_e64 v36, v1, v0, s[2:3]
	v_add_u32_e32 v36, v36, v151
	s_nop 0
	s_waitcnt lgkmcnt(1)
	v_mfma_f32_16x16x32_f16 v[68:71], v[76:79], v[68:71], 0
	v_mfma_f32_16x16x32_f16 v[86:89], v[76:79], v[86:89], 0
	s_nop 2
	v_cvt_f16_f32_e32 v1, v82
	v_cvt_f16_f32_e32 v2, v83
	v_cvt_f16_f32_e32 v66, v85
	v_mfma_f32_16x16x32_f16 v[72:75], v[90:93], v[94:97], v[72:75]
	v_mov_b32_e32 v85, v3
	v_cndmask_b32_e64 v66, 0, v66, s[22:23]
	s_nop 0
	s_waitcnt lgkmcnt(0)
	v_mfma_f32_16x16x32_f16 v[76:79], v[90:93], v[126:129], v[62:65]
	v_mov_b32_e32 v92, v3
	s_nop 2
	v_cndmask_b32_e64 v0, 0, v72, s[10:11]
	v_cndmask_b32_e64 v37, 0, v73, s[14:15]
	v_cvt_f16_f32_e32 v63, v84
	v_mfma_f32_16x16x32_f16 v[94:97], v[98:101], v[94:97], v[68:71]
	v_cndmask_b32_e64 v64, 0, v74, s[16:17]
	v_cndmask_b32_e64 v65, 0, v75, s[20:21]
	v_cndmask_b32_e64 v63, 0, v63, s[18:19]
	v_cndmask_b32_e64 v68, 0, v1, s[12:13]
	v_cndmask_b32_e64 v69, v2, 0, s[10:11]
	v_add_f32_e32 v62, v213, v0
	v_cvt_pk_f16_f32 v1, v64, v65
	v_cvt_pk_f16_f32 v0, v0, v37
	v_mov_b32_e32 v2, v3
	v_pack_b32_f16 v67, v63, v66
	v_pack_b32_f16 v66, v68, v69
	v_mov_b32_e32 v68, v3
	v_mov_b32_e32 v69, v3
	v_add_f32_e32 v63, v214, v37
	v_add_f32_e32 v64, v215, v64
	v_mfma_f32_16x16x32_f16 v[70:73], v[0:3], v[66:69], 0
	v_add_f32_e32 v65, v216, v65
	v_cvt_pk_f16_f32 v83, v64, v65
	v_cvt_pk_f16_f32 v82, v62, v63
	v_mfma_f32_16x16x32_f16 v[66:69], v[66:69], v[0:3], 0
	v_mov_b32_e32 v84, v3
	s_nop 2
	v_cvt_pk_f16_f32 v0, v70, v71
	v_mov_b32_e32 v70, v3
	v_mov_b32_e32 v71, v3
	v_cvt_pk_f16_f32 v1, v72, v73
	v_cvt_pk_f16_f32 v69, v68, v69
	v_cvt_pk_f16_f32 v68, v66, v67
	v_mfma_f32_16x16x32_f16 v[62:65], v[0:3], v[82:85], v[62:65]
	v_mad_i64_i32 v[36:37], s[26:27], v36, s88, v[122:123]
	global_store_short v[36:37], v60, off
	v_mfma_f32_16x16x32_f16 v[72:75], v[68:71], v[0:3], 0
	v_cvt_f16_f32_e32 v82, v61
	v_subrev_u32_e32 v36, 61, v80
	v_xad_u32 v37, v102, -4, v172
	v_mfma_f32_16x16x32_f16 v[66:69], v[0:3], v[68:71], 0
	s_nop 0
	v_cvt_pk_f16_f32 v71, v64, v65
	s_nop 1
	v_cvt_pk_f16_f32 v1, v74, v75
	v_cvt_pk_f16_f32 v0, v72, v73
	ds_read2_b64 v[134:137], v224 offset1:4
	v_mfma_f32_16x16x32_f16 v[56:59], v[98:101], v[126:129], v[86:89]
	v_cvt_pk_f16_f32 v70, v62, v63
	v_mov_b32_e32 v72, v3
	v_mov_b32_e32 v73, v3
	v_cvt_pk_f16_f32 v85, v68, v69
	ds_read2_b64 v[126:129], v224 offset0:8 offset1:12
	v_cvt_pk_f16_f32 v84, v66, v67
	v_mov_b32_e32 v86, v3
	v_mov_b32_e32 v87, v3
	v_mfma_f32_16x16x32_f16 v[88:91], v[0:3], v[70:73], v[62:65]
	s_nop 0
	s_nop 0
	v_cndmask_b32_e64 v36, v37, v36, s[2:3]
	v_mfma_f32_16x16x32_f16 v[60:63], v[84:87], v[0:3], 0
	v_add_u32_e32 v83, v36, v151
	s_nop 2
	v_cvt_pk_f16_f32 v1, v90, v91
	v_cvt_pk_f16_f32 v0, v88, v89
	v_cvt_pk_f16_f32 v67, v54, v55
	v_cvt_pk_f16_f32 v66, v52, v53
	v_cvt_pk_f16_f32 v85, v62, v63
	v_cvt_pk_f16_f32 v84, v60, v61
	v_cvt_pk_f16_f32 v63, v50, v51
	v_cvt_pk_f16_f32 v62, v48, v49
	v_cvt_pk_f16_f32 v61, v42, v43
	v_cvt_pk_f16_f32 v60, v40, v41
	v_cvt_pk_f16_f32 v65, v46, v47
	v_cvt_pk_f16_f32 v64, v44, v45
	s_nop 0
	s_waitcnt lgkmcnt(1)
	v_mfma_f32_16x16x32_f16 v[68:71], v[134:137], v[60:63], 0
	v_add_u32_e32 v36, 0x1000, v224
	v_mov_b32_e32 v93, v3
	v_cvt_f16_f32_e32 v76, v76
	s_nop 0
	s_waitcnt lgkmcnt(0)
	v_mfma_f32_16x16x32_f16 v[98:101], v[126:129], v[64:67], v[68:71]
	ds_read2_b64 v[72:75], v36 offset0:64 offset1:68
	s_nop 1
	ds_read2_b64 v[68:71], v36 offset0:72 offset1:76
	v_cvt_f16_f32_e32 v36, v97
	v_cvt_f16_f32_e32 v97, v77
	v_mfma_f32_16x16x32_f16 v[84:87], v[84:87], v[0:3], v[88:91]
	v_cvt_f16_f32_e32 v0, v94
	v_cvt_f16_f32_e32 v1, v95
	v_cvt_f16_f32_e32 v2, v96
	v_cndmask_b32_e64 v96, v76, 0, s[12:13]
	v_cndmask_b32_e64 v0, 0, v0, s[10:11]
	v_cndmask_b32_e64 v37, 0, v1, s[14:15]
	v_cndmask_b32_e64 v1, 0, v2, s[16:17]
	v_cndmask_b32_e64 v2, 0, v36, s[20:21]
	v_pack_b32_f16 v1, v1, v2
	v_pack_b32_f16 v0, v0, v37
	v_mov_b32_e32 v2, v3
	v_mov_b32_e32 v36, v132
	v_mov_b32_e32 v37, v133
	v_mov_b32_e32 v38, v3
	v_mov_b32_e32 v39, v3
	v_mov_b32_e32 v94, v3
	v_mov_b32_e32 v95, v3
	v_mfma_f32_16x16x32_f16 v[88:91], v[0:3], v[36:39], v[98:101]
	v_cvt_pk_f16_f32 v1, v86, v87
	v_cvt_pk_f16_f32 v0, v84, v85
	v_cvt_f16_f32_e32 v56, v56
	v_cvt_f16_f32_e32 v98, v78
	v_cvt_f16_f32_e32 v99, v79
	s_nop 2
	v_cvt_pk_f16_f32 v91, v90, v91
	v_cvt_pk_f16_f32 v90, v88, v89
	v_cndmask_b32_e64 v97, 0, v97, s[10:11]
	v_cndmask_b32_e64 v98, v98, 0, s[18:19]
	v_mfma_f32_16x16x32_f16 v[84:87], v[0:3], v[90:93], 0
	v_add_u32_e32 v2, 0x800, v233
	ds_read2_b64 v[126:129], v2 offset0:64 offset1:144
	ds_read_b128 v[76:79], v178 offset:256
	v_mov_b32_e32 v90, v3
	v_mov_b32_e32 v91, v3
	v_cndmask_b32_e64 v99, v99, 0, s[22:23]
	ds_read_b64 v[88:89], v225 offset:5120
	ds_read_b128 v[130:133], v178 offset:320
	s_nop 3
	v_cvt_pk_f16_f32 v1, v86, v87
	v_cvt_pk_f16_f32 v0, v84, v85
	s_nop 0
	s_nop 0
	s_nop 0
	v_mov_b32_e32 v2, v3
	s_nop 0
	s_waitcnt lgkmcnt(3)
	v_mov_b32_e32 v92, v126
	v_mov_b32_e32 v93, v127
	ds_read_b64 v[84:85], v226 offset:5120
	s_nop 0
	s_waitcnt lgkmcnt(3)
	v_pk_mul_f32 v[42:43], v[42:43], v[78:79]
	v_pk_mul_f32 v[40:41], v[40:41], v[76:77]
	s_nop 0
	s_nop 0
	v_mfma_f32_16x16x32_f16 v[40:43], v[92:95], v[0:3], v[40:43]
	s_nop 0
	s_waitcnt lgkmcnt(1)
	v_pk_mul_f32 v[48:49], v[48:49], v[130:131]
	v_add_u32_e32 v76, 0xc00, v233
	ds_read2_b64 v[134:137], v227 offset1:80
	ds_read_b128 v[138:141], v178 offset:384
	v_mfma_f32_16x16x32_f16 v[40:43], v[88:91], v[36:39], v[40:43]
	v_mov_b32_e32 v88, v128
	v_mov_b32_e32 v89, v129
	v_pk_mul_f32 v[50:51], v[50:51], v[132:133]
	v_mov_b32_e32 v86, v3
	v_mov_b32_e32 v87, v3
	s_nop 0
	v_mfma_f32_16x16x32_f16 v[48:51], v[88:91], v[0:3], v[48:51]
	ds_read_b64 v[88:89], v227 offset:5120
	s_nop 0
	s_waitcnt lgkmcnt(2)
	v_mov_b32_e32 v92, v134
	v_mfma_f32_16x16x32_f16 v[48:51], v[84:87], v[36:39], v[48:51]
	s_nop 0
	s_nop 0
	v_mov_b32_e32 v93, v135
	v_pack_b32_f16 v76, v96, v97
	v_cndmask_b32_e64 v96, v56, 0, s[12:13]
	s_nop 0
	s_waitcnt lgkmcnt(1)
	v_pk_mul_f32 v[46:47], v[46:47], v[140:141]
	v_pk_mul_f32 v[44:45], v[44:45], v[138:139]
	ds_read_b128 v[84:87], v178 offset:448
	v_cvt_f16_f32_e32 v56, v57
	v_cvt_f16_f32_e32 v57, v58
	v_mfma_f32_16x16x32_f16 v[44:47], v[92:95], v[0:3], v[44:47]
	v_cvt_f16_f32_e32 v58, v59
	v_mov_b32_e32 v92, v136
	v_mov_b32_e32 v93, v137
	s_nop 0
	s_waitcnt lgkmcnt(1)
	v_mfma_f32_16x16x32_f16 v[44:47], v[88:91], v[36:39], v[44:47]
	ds_read_b64 v[88:89], v228 offset:5120
	s_nop 0
	s_nop 0
	v_cndmask_b32_e64 v78, v57, 0, s[18:19]
	v_cndmask_b32_e64 v79, v58, 0, s[22:23]
	v_pack_b32_f16 v77, v98, v99
	s_nop 0
	s_waitcnt lgkmcnt(1)
	v_pk_mul_f32 v[52:53], v[52:53], v[84:85]
	v_cndmask_b32_e64 v84, 0, v56, s[10:11]
	v_mfma_f32_16x16x32_f16 v[56:59], v[72:75], v[60:63], 0
	v_pack_b32_f16 v61, v78, v79
	v_mov_b32_e32 v78, v3
	v_mov_b32_e32 v79, v3
	v_mfma_f32_16x16x32_f16 v[56:59], v[68:71], v[64:67], v[56:59]
	v_mul_f32_e64 v54, v54, v86
	v_mul_f32_e64 v55, v55, v87
	v_pack_b32_f16 v60, v96, v84
	v_mov_b32_e32 v62, v3
	v_mov_b32_e32 v63, v3
	v_mfma_f32_16x16x32_f16 v[52:55], v[92:95], v[0:3], v[52:55]
	v_mfma_f32_16x16x32_f16 v[56:59], v[76:79], v[0:3], v[56:59]
	v_mad_i64_i32 v[0:1], s[26:27], v83, s88, v[122:123]
	global_store_short v[0:1], v82, off
	s_nop 0
	s_waitcnt lgkmcnt(0)
	v_mfma_f32_16x16x32_f16 v[52:55], v[88:91], v[36:39], v[52:55]
	v_subrev_u32_e32 v0, 48, v80
	v_add_u32_e32 v1, 0x7ef, v81
	v_cndmask_b32_e64 v0, v1, v0, s[2:3]
	v_mfma_f32_16x16x32_f16 v[36:39], v[60:63], v[36:39], v[56:59]
	v_add_u32_e32 v0, v0, v151
	v_mad_i64_i32 v[0:1], s[26:27], v0, s88, v[122:123]
	s_nop 5
	v_cvt_f16_f32_e32 v2, v36
	global_store_short v[0:1], v2, off
	v_subrev_u32_e32 v0, 47, v80
	v_add_u32_e32 v1, 0x7ee, v81
	v_cvt_f16_f32_e32 v2, v37
	v_cndmask_b32_e64 v0, v1, v0, s[2:3]
	v_add_u32_e32 v0, v0, v151
	v_mad_i64_i32 v[0:1], s[26:27], v0, s88, v[122:123]
	global_store_short v[0:1], v2, off
	v_subrev_u32_e32 v0, 46, v80
	v_add_u32_e32 v1, 0x7ed, v81
	v_cvt_f16_f32_e32 v2, v38
	v_cndmask_b32_e64 v0, v1, v0, s[2:3]
	v_add_u32_e32 v0, v0, v151
	v_mad_i64_i32 v[0:1], s[26:27], v0, s88, v[122:123]
	global_store_short v[0:1], v2, off
	v_subrev_u32_e32 v0, 45, v80
	v_add_u32_e32 v1, 0x7ec, v81
	v_cndmask_b32_e64 v0, v1, v0, s[2:3]
	v_cvt_f16_f32_e32 v2, v39
	v_add_u32_e32 v0, v0, v151
	v_mad_i64_i32 v[0:1], s[26:27], v0, s88, v[122:123]
	s_mov_b64 s[26:27], 0
	global_store_short v[0:1], v2, off
